# SWA: all three sinks scalars loaded with head 0 (heads 1,2 no longer wait on VMEM); conv data loads issued right after head 0's wait so they overlap the whole SWA compute
# speedup vs baseline: 1.0027x; 1.0027x over previous
; __device__ __forceinline__ unsigned cvt_pk_bf16(float lo, float hi) { unsigned r; asm volatile("v_cvt_pk_bf16_f32 %0, %1, %2" : "=v"(r) : "v"(lo), "v"(hi)); return r; }
; __device__ __forceinline__ void swa_item(LAS unsigned char* lds, const GAS bf16_t* proj, GAS bf16_t* mix, const GAS float* sinks, int nb, int hk, int tid, int w, int lane) {
;     ...
;         const float sink = sinks[hq];
;         float mx = sink;
; #pragma unroll
;         for (int j = 0; j < 9; ++j)
; #pragma unroll
;             for (int i = 0; i < 4; ++i) { const int kpos = 16 * (w + j) + 4 * fq + i;
;                 if (j == 0) s[j][i] = kpos > ql ? s[j][i] : -1e30f;
;                 if (j == 8) s[j][i] = kpos <= ql + 128 ? s[j][i] : -1e30f; }
;         if (nb == 0) {
; #pragma unroll
;             for (int j = 0; j < 9; ++j)
; #pragma unroll
;                 for (int i = 0; i < 4; ++i) s[j][i] = (16 * (w + j) + 4 * fq + i) >= 128 ? s[j][i] : -1e30f;
;         }
; #pragma unroll
;         for (int j = 0; j < 9; ++j)
; #pragma unroll
;             for (int i = 0; i < 4; ++i) mx = fmaxf(mx, s[j][i]);
;         mx = fmaxf(mx, __shfl_xor(mx, 16)); mx = fmaxf(mx, __shfl_xor(mx, 32));
;         float sum = 0.f; const float nmx = -mx * 1.4426950408889634f;
; #pragma unroll
;         for (int j = 0; j < 9; ++j)
; #pragma unroll
;             for (int i = 0; i < 4; ++i) { const float p = __builtin_amdgcn_exp2f(__builtin_fmaf(s[j][i], 1.4426950408889634f, nmx)); s[j][i] = p; sum += p; }
;         sum += __shfl_xor(sum, 16); sum += __shfl_xor(sum, 32);
;         const float inv = __builtin_amdgcn_rcpf(sum + __expf(sink - mx));
;         f32x4 o[4];
; #pragma unroll
;         for (int et = 0; et < 4; ++et) o[et] = (f32x4){0.f, 0.f, 0.f, 0.f};
; #pragma unroll
;         for (int jj = 0; jj < 5; ++jj) {
;             const int j0 = 2 * jj, j1 = 2 * jj + 1;
;             u32x2 plo, phi; plo.x = cvt_pk_bf16(s[j0][0], s[j0][1]); plo.y = cvt_pk_bf16(s[j0][2], s[j0][3]);
;             if (j1 < 9) { phi.x = cvt_pk_bf16(s[j1 < 9 ? j1 : 0][0], s[j1 < 9 ? j1 : 0][1]); phi.y = cvt_pk_bf16(s[j1 < 9 ? j1 : 0][2], s[j1 < 9 ? j1 : 0][3]); } else { phi.x = 0u; phi.y = 0u; }
;             const bf16x8 pb = mk8(plo, phi);
; #pragma unroll
.LBB0_411:
	s_nop 0
	v_max3_f32 v5, v4, v41, v40
	v_max3_f32 v5, v5, v11, v10
	v_max3_f32 v5, v5, v36, v37
	v_max3_f32 v5, v5, v38, v39
	v_max3_f32 v5, v5, v32, v33
	v_max3_f32 v5, v5, v34, v35
	v_max3_f32 v5, v5, v28, v29
	v_max3_f32 v5, v5, v30, v31
	v_max3_f32 v5, v5, v24, v25
	v_max3_f32 v5, v5, v26, v27
	v_max3_f32 v5, v5, v20, v21
	v_max3_f32 v5, v5, v22, v23
	v_max3_f32 v5, v5, v12, v13
	v_max3_f32 v5, v5, v14, v15
	v_max3_f32 v5, v5, v16, v17
	v_max3_f32 v5, v5, v18, v19
	v_max3_f32 v5, v5, v9, v8
	v_max3_f32 v5, v5, v7, v6
	ds_bpermute_b32 v42, v75, v5
	s_lshl_b32 s0, s59, 8
	s_addk_i32 s0, 0x600
	v_readlane_b32 s60, v254, 55
	v_readlane_b32 s61, v254, 56
	s_waitcnt lgkmcnt(0)
	v_max_f32_e32 v42, v42, v42
	v_max_f32_e32 v5, v5, v42
	ds_bpermute_b32 v42, v76, v5
	s_mov_b64 s[62:63], s[64:65]
	s_waitcnt lgkmcnt(0)
	v_max_f32_e32 v42, v42, v42
	v_max_f32_e32 v5, v5, v42
	v_mul_f32_e32 v42, 0xbfb8aa3b, v5
	v_fmamk_f32 v41, v41, 0x3fb8aa3b, v42
	v_exp_f32_e32 v41, v41
	v_fmamk_f32 v40, v40, 0x3fb8aa3b, v42
	v_exp_f32_e32 v40, v40
	v_fmamk_f32 v11, v11, 0x3fb8aa3b, v42
	v_exp_f32_e32 v44, v11
	v_add_f32_e32 v43, 0, v41
	v_add_f32_e32 v43, v40, v43
	v_fmamk_f32 v10, v10, 0x3fb8aa3b, v42
	v_add_f32_e32 v11, v44, v43
	v_exp_f32_e32 v43, v10
	v_fmamk_f32 v9, v9, 0x3fb8aa3b, v42
	v_exp_f32_e32 v9, v9
	v_fmamk_f32 v8, v8, 0x3fb8aa3b, v42
	v_add_f32_e32 v10, v43, v11
	v_fmamk_f32 v11, v36, 0x3fb8aa3b, v42
	v_exp_f32_e32 v36, v11
	v_fmamk_f32 v11, v37, 0x3fb8aa3b, v42
	v_exp_f32_e32 v37, v11
	v_fmamk_f32 v11, v38, 0x3fb8aa3b, v42
	v_exp_f32_e32 v38, v11
	v_fmamk_f32 v11, v39, 0x3fb8aa3b, v42
	v_exp_f32_e32 v39, v11
	v_fmamk_f32 v11, v32, 0x3fb8aa3b, v42
	v_exp_f32_e32 v32, v11
	v_fmamk_f32 v11, v33, 0x3fb8aa3b, v42
	v_exp_f32_e32 v33, v11
	v_fmamk_f32 v11, v34, 0x3fb8aa3b, v42
	v_exp_f32_e32 v34, v11
	v_fmamk_f32 v11, v35, 0x3fb8aa3b, v42
	v_exp_f32_e32 v35, v11
	v_fmamk_f32 v11, v28, 0x3fb8aa3b, v42
	v_exp_f32_e32 v45, v11
	v_fmamk_f32 v11, v29, 0x3fb8aa3b, v42
	v_exp_f32_e32 v46, v11
	v_fmamk_f32 v11, v30, 0x3fb8aa3b, v42
	v_exp_f32_e32 v47, v11
	v_fmamk_f32 v11, v31, 0x3fb8aa3b, v42
	v_exp_f32_e32 v48, v11
	v_fmamk_f32 v11, v24, 0x3fb8aa3b, v42
	v_exp_f32_e32 v51, v11
	v_fmamk_f32 v11, v25, 0x3fb8aa3b, v42
	v_exp_f32_e32 v52, v11
	v_fmamk_f32 v11, v26, 0x3fb8aa3b, v42
	v_exp_f32_e32 v53, v11
	v_fmamk_f32 v11, v27, 0x3fb8aa3b, v42
	v_exp_f32_e32 v54, v11
	v_fmamk_f32 v11, v20, 0x3fb8aa3b, v42
	v_exp_f32_e32 v55, v11
	v_fmamk_f32 v11, v21, 0x3fb8aa3b, v42
	v_exp_f32_e32 v56, v11
	v_fmamk_f32 v11, v22, 0x3fb8aa3b, v42
	v_exp_f32_e32 v57, v11
	v_fmamk_f32 v11, v23, 0x3fb8aa3b, v42
	v_exp_f32_e32 v58, v11
	v_fmamk_f32 v11, v12, 0x3fb8aa3b, v42
	v_exp_f32_e32 v59, v11
	v_fmamk_f32 v11, v13, 0x3fb8aa3b, v42
	v_exp_f32_e32 v66, v11
	v_fmamk_f32 v11, v14, 0x3fb8aa3b, v42
	v_exp_f32_e32 v67, v11
	v_fmamk_f32 v11, v15, 0x3fb8aa3b, v42
	v_exp_f32_e32 v132, v11
	v_fmamk_f32 v11, v16, 0x3fb8aa3b, v42
	v_add_f32_e32 v10, v36, v10
	v_exp_f32_e32 v133, v11
	v_fmamk_f32 v11, v17, 0x3fb8aa3b, v42
	v_add_f32_e32 v10, v37, v10
	v_exp_f32_e32 v134, v11
	v_fmamk_f32 v11, v18, 0x3fb8aa3b, v42
	v_add_f32_e32 v10, v38, v10
	v_exp_f32_e32 v135, v11
	v_fmamk_f32 v11, v19, 0x3fb8aa3b, v42
	v_cvt_pk_bf16_f32 v12, v41, v40
	v_cvt_pk_bf16_f32 v13, v44, v43
	v_cvt_pk_bf16_f32 v14, v36, v37
	v_cvt_pk_bf16_f32 v15, v38, v39
	ds_read_b64 v[16:17], v77 offset:36864
	ds_read_b64 v[18:19], v78 offset:36864
	ds_read_b64 v[20:21], v79 offset:36864
	ds_read_b64 v[22:23], v80 offset:36864
	ds_read_b64 v[24:25], v81 offset:36864
	ds_read_b64 v[26:27], v82 offset:36864
	ds_read_b64 v[28:29], v83 offset:36864
	ds_read_b64 v[30:31], v84 offset:36864
	v_add_f32_e32 v10, v39, v10
	v_add_f32_e32 v10, v32, v10
	v_add_f32_e32 v10, v33, v10
	v_add_f32_e32 v10, v34, v10
	v_add_f32_e32 v10, v35, v10
	s_waitcnt lgkmcnt(6)
	v_mfma_f32_16x16x32_bf16 v[16:19], v[16:19], v[12:15], 0
	v_add_f32_e32 v10, v45, v10
	v_add_f32_e32 v10, v46, v10
	v_add_f32_e32 v10, v47, v10
	s_waitcnt lgkmcnt(4)
	v_mfma_f32_16x16x32_bf16 v[20:23], v[20:23], v[12:15], 0
	v_add_f32_e32 v10, v48, v10
	v_add_f32_e32 v10, v51, v10
	v_add_f32_e32 v10, v52, v10
	s_waitcnt lgkmcnt(2)
	v_mfma_f32_16x16x32_bf16 v[24:27], v[24:27], v[12:15], 0
	v_add_f32_e32 v10, v53, v10
	v_add_f32_e32 v10, v54, v10
	v_add_f32_e32 v10, v55, v10
	s_waitcnt lgkmcnt(0)
	v_mfma_f32_16x16x32_bf16 v[12:15], v[28:31], v[12:15], 0
	v_cvt_pk_bf16_f32 v28, v32, v33
	v_cvt_pk_bf16_f32 v29, v34, v35
	v_cvt_pk_bf16_f32 v30, v45, v46
	v_cvt_pk_bf16_f32 v31, v47, v48
	ds_read_b64 v[32:33], v85 offset:36864
	ds_read_b64 v[34:35], v86 offset:36864
	s_waitcnt lgkmcnt(0)
	v_mfma_f32_16x16x32_bf16 v[16:19], v[32:35], v[28:31], v[16:19]
	ds_read_b64 v[32:33], v87 offset:36864
	ds_read_b64 v[34:35], v88 offset:36864
	v_add_f32_e32 v10, v56, v10
	v_add_f32_e32 v10, v57, v10
	s_waitcnt lgkmcnt(0)
; __device__ __forceinline__ unsigned cvt_pk_bf16(float lo, float hi) { unsigned r; asm volatile("v_cvt_pk_bf16_f32 %0, %1, %2" : "=v"(r) : "v"(lo), "v"(hi)); return r; }
; #define LAS __attribute__((address_space(3)))
; #define GAS __attribute__((address_space(1)))
; __device__ __forceinline__ size_t TX(int row, int col) { return ((((size_t)(row >> 8) * 16 + (col >> 6)) * 256 + (row & 255)) << 6) + (col & 63); }
; __device__ __forceinline__ int tsw(int d) { return ((d >> 3) & 7) << 3; }
; #define MFMA16(a, b, c) __builtin_amdgcn_mfma_f32_16x16x32_bf16(a, b, c, 0, 0, 0)
; __device__ __forceinline__ void swa_item(LAS unsigned char* lds, const GAS bf16_t* proj, GAS bf16_t* mix, const GAS float* sinks, int nb, int hk, int tid, int w, int lane) {
;     ...
; #pragma unroll
;         for (int jj = 0; jj < 5; ++jj) {
;             const int j0 = 2 * jj, j1 = 2 * jj + 1;
;             u32x2 plo, phi; plo.x = cvt_pk_bf16(s[j0][0], s[j0][1]); plo.y = cvt_pk_bf16(s[j0][2], s[j0][3]);
;             if (j1 < 9) { phi.x = cvt_pk_bf16(s[j1 < 9 ? j1 : 0][0], s[j1 < 9 ? j1 : 0][1]); phi.y = cvt_pk_bf16(s[j1 < 9 ? j1 : 0][2], s[j1 < 9 ? j1 : 0][3]); } else { phi.x = 0u; phi.y = 0u; }
;             const bf16x8 pb = mk8(plo, phi);
; #pragma unroll
;             for (int et = 0; et < 4; ++et) {
;                 const LAS bf16_t* vr = VTs + (16 * et + fr) * VS; const int sw = tsw(16 * et + fr), kc0 = 16 * (w + j0) + 4 * fq;
;                 const u32x2 a0 = *(const LAS u32x2*)(vr + (kc0 ^ sw)), a1 = *(const LAS u32x2*)(vr + ((kc0 + 16) ^ sw));
;                 o[et] = MFMA16(mk8(a0, a1), pb, o[et]);
;             }
;         }
; #pragma unroll
;         for (int et = 0; et < 4; ++et) { const f32x4 v = o[et] * inv; u32x2 wv; wv.x = cvt_pk_bf16(v[0], v[1]); wv.y = cvt_pk_bf16(v[2], v[3]);
;             *(GAS u32x2*)(mix + TX(tq, MIX_SWA + 64 * hq + 16 * et + 4 * fq)) = wv; }
;     }
;     __syncthreads();
	v_mfma_f32_16x16x32_bf16 v[20:23], v[32:35], v[28:31], v[20:23]
	ds_read_b64 v[32:33], v89 offset:36864
	ds_read_b64 v[34:35], v90 offset:36864
	v_add_f32_e32 v10, v58, v10
	v_add_f32_e32 v10, v59, v10
	s_waitcnt lgkmcnt(0)
	v_mfma_f32_16x16x32_bf16 v[24:27], v[32:35], v[28:31], v[24:27]
	ds_read_b64 v[32:33], v91 offset:36864
	ds_read_b64 v[34:35], v92 offset:36864
	v_add_f32_e32 v10, v66, v10
	v_add_f32_e32 v10, v67, v10
	s_waitcnt lgkmcnt(0)
	v_mfma_f32_16x16x32_bf16 v[12:15], v[32:35], v[28:31], v[12:15]
	v_cvt_pk_bf16_f32 v28, v51, v52
	v_cvt_pk_bf16_f32 v29, v53, v54
	v_cvt_pk_bf16_f32 v30, v55, v56
	v_cvt_pk_bf16_f32 v31, v57, v58
	ds_read_b64 v[32:33], v93 offset:36864
	ds_read_b64 v[34:35], v94 offset:36864
	s_waitcnt lgkmcnt(0)
	v_mfma_f32_16x16x32_bf16 v[16:19], v[32:35], v[28:31], v[16:19]
	ds_read_b64 v[32:33], v95 offset:36864
	ds_read_b64 v[34:35], v96 offset:36864
	v_add_f32_e32 v10, v132, v10
	v_exp_f32_e32 v136, v11
	s_waitcnt lgkmcnt(0)
	v_mfma_f32_16x16x32_bf16 v[20:23], v[32:35], v[28:31], v[20:23]
	ds_read_b64 v[32:33], v97 offset:36864
	ds_read_b64 v[34:35], v98 offset:36864
	v_add_f32_e32 v10, v133, v10
	v_add_f32_e32 v10, v134, v10
	s_waitcnt lgkmcnt(0)
	v_mfma_f32_16x16x32_bf16 v[24:27], v[32:35], v[28:31], v[24:27]
	ds_read_b64 v[32:33], v99 offset:36864
	ds_read_b64 v[34:35], v100 offset:36864
	v_exp_f32_e32 v8, v8
	v_add_f32_e32 v10, v135, v10
	s_waitcnt lgkmcnt(0)
	v_mfma_f32_16x16x32_bf16 v[12:15], v[32:35], v[28:31], v[12:15]
	v_cvt_pk_bf16_f32 v28, v59, v66
	v_cvt_pk_bf16_f32 v29, v67, v132
	v_cvt_pk_bf16_f32 v30, v133, v134
	v_cvt_pk_bf16_f32 v31, v135, v136
	ds_read_b64 v[32:33], v101 offset:36864
	ds_read_b64 v[34:35], v102 offset:36864
	v_add_f32_e32 v10, v136, v10
	v_add_f32_e32 v10, v9, v10
	v_fmamk_f32 v7, v7, 0x3fb8aa3b, v42
	v_add_f32_e32 v11, v8, v10
	v_exp_f32_e32 v10, v7
	s_waitcnt lgkmcnt(0)
	v_mfma_f32_16x16x32_bf16 v[16:19], v[32:35], v[28:31], v[16:19]
	ds_read_b64 v[32:33], v103 offset:36864
	ds_read_b64 v[34:35], v104 offset:36864
	v_fmac_f32_e32 v42, 0x3fb8aa3b, v6
	v_add_f32_e32 v7, v10, v11
	v_exp_f32_e32 v11, v42
	s_waitcnt lgkmcnt(0)
	v_mfma_f32_16x16x32_bf16 v[20:23], v[32:35], v[28:31], v[20:23]
	ds_read_b64 v[32:33], v105 offset:36864
	ds_read_b64 v[34:35], v106 offset:36864
	v_add_f32_e32 v6, v11, v7
	ds_bpermute_b32 v7, v75, v6
	s_waitcnt lgkmcnt(1)
	v_mfma_f32_16x16x32_bf16 v[24:27], v[32:35], v[28:31], v[24:27]
	ds_read_b64 v[32:33], v107 offset:36864
	ds_read_b64 v[34:35], v108 offset:36864
	s_waitcnt lgkmcnt(2)
	v_add_f32_e32 v6, v6, v7
	ds_bpermute_b32 v7, v76, v6
	v_sub_f32_e32 v4, v4, v5
	v_mul_f32_e32 v4, 0x3fb8aa3b, v4
	s_waitcnt lgkmcnt(1)
	v_mfma_f32_16x16x32_bf16 v[12:15], v[32:35], v[28:31], v[12:15]
	v_cvt_pk_bf16_f32 v8, v9, v8
	v_cvt_pk_bf16_f32 v9, v10, v11
	ds_read_b64 v[30:31], v116 offset:36864
	ds_read_b64 v[28:29], v115 offset:36864
	ds_read_b64 v[34:35], v114 offset:36864
	ds_read_b64 v[32:33], v113 offset:36864
	ds_read_b64 v[38:39], v112 offset:36864
	ds_read_b64 v[36:37], v111 offset:36864
	ds_read_b64 v[42:43], v110 offset:36864
	ds_read_b64 v[40:41], v109 offset:36864
	v_exp_f32_e32 v4, v4
	s_waitcnt lgkmcnt(8)
	v_add_f32_e32 v5, v6, v7
	v_mov_b32_e32 v10, v179
	v_mov_b32_e32 v11, v179
	v_add_f32_e32 v44, v4, v5
	v_or_b32_e32 v48, s0, v50
	s_waitcnt lgkmcnt(0)
	v_mfma_f32_16x16x32_bf16 v[4:7], v[40:43], v[8:11], v[16:19]
	v_readlane_b32 s0, v254, 50
	s_add_i32 s58, s58, s0
	s_cmpk_gt_i32 s58, 0xff
	v_mfma_f32_16x16x32_bf16 v[16:19], v[36:39], v[8:11], v[20:23]
	v_mfma_f32_16x16x32_bf16 v[20:23], v[32:35], v[8:11], v[24:27]
	v_mfma_f32_16x16x32_bf16 v[8:11], v[28:31], v[8:11], v[12:15]
	s_nop 2
	v_rcp_f32_e32 v12, v44
	v_lshlrev_b64 v[14:15], 7, v[48:49]
	v_pk_mul_f32 v[6:7], v[6:7], v[12:13] op_sel_hi:[1,0]
	v_pk_mul_f32 v[4:5], v[4:5], v[12:13] op_sel_hi:[1,0]
	s_nop 0
	v_pk_mul_f32 v[8:9], v[8:9], v[12:13] op_sel_hi:[1,0]
	v_cvt_pk_bf16_f32 v4, v4, v5
	v_cvt_pk_bf16_f32 v5, v6, v7
	v_lshl_add_u64 v[6:7], v[64:65], 0, v[14:15]
	v_pk_mul_f32 v[14:15], v[16:17], v[12:13] op_sel_hi:[1,0]
	global_store_dwordx2 v[6:7], v[4:5], off
	v_pk_mul_f32 v[4:5], v[18:19], v[12:13] op_sel_hi:[1,0]
	v_cvt_pk_bf16_f32 v14, v14, v15
	s_nop 0
	v_cvt_pk_bf16_f32 v15, v4, v5
	global_store_dwordx2 v[6:7], v[14:15], off offset:32
	v_pk_mul_f32 v[4:5], v[22:23], v[12:13] op_sel_hi:[1,0]
	v_pk_mul_f32 v[14:15], v[20:21], v[12:13] op_sel_hi:[1,0]
	s_nop 0
	v_cvt_pk_bf16_f32 v14, v14, v15
	v_cvt_pk_bf16_f32 v15, v4, v5
	global_store_dwordx2 v[6:7], v[14:15], off offset:64
	v_pk_mul_f32 v[4:5], v[10:11], v[12:13] op_sel_hi:[1,0]
	v_cvt_pk_bf16_f32 v8, v8, v9
	s_nop 0
	v_cvt_pk_bf16_f32 v9, v4, v5
	global_store_dwordx2 v[6:7], v[8:9], off offset:96
	s_barrier
	s_cbranch_scc1 .LBB0_434

; #define LAS __attribute__((address_space(3)))
; #define MFMA16(a, b, c) __builtin_amdgcn_mfma_f32_16x16x32_bf16(a, b, c, 0, 0, 0)
; __device__ __forceinline__ void swa_item(LAS unsigned char* lds, const GAS bf16_t* proj, GAS bf16_t* mix, const GAS float* sinks, int nb, int hk, int tid, int w, int lane) {
;     ...
;     for (int g = 0; g < 3; ++g) {
;         const int hq = 3 * hk + g;
;         bf16x8 qf[2]; qf[0] = qfa[g][0]; qf[1] = qfa[g][1];
;         f32x4 s[9];
; #pragma unroll
;         for (int j = 0; j < 9; ++j) { s[j] = (f32x4){0.f, 0.f, 0.f, 0.f};
; #pragma unroll
;             for (int c = 0; c < 2; ++c) { const bf16x8 a = *(const LAS bf16x8*)(Ks + (16 * (w + j) + fr) * KS + 32 * c + 8 * fq); s[j] = MFMA16(a, qf[c], s[j]); } }
;         const float sink = sinks[hq];
;         float mx = sink;
; #pragma unroll
;         for (int j = 0; j < 9; ++j)
; #pragma unroll
;             for (int i = 0; i < 4; ++i) { const int kpos = 16 * (w + j) + 4 * fq + i;
;                 if (j == 0) s[j][i] = kpos > ql ? s[j][i] : -1e30f;
;                 if (j == 8) s[j][i] = kpos <= ql + 128 ? s[j][i] : -1e30f; }
;         if (nb == 0) {
; #pragma unroll
;             for (int j = 0; j < 9; ++j)
; #pragma unroll
;                 for (int i = 0; i < 4; ++i) s[j][i] = (16 * (w + j) + 4 * fq + i) >= 128 ? s[j][i] : -1e30f;
;         }
.LBB0_428:
	s_or_b64 exec, exec, s[0:1]
	s_waitcnt lgkmcnt(0)
	s_barrier
	ds_read_b128 v[20:23], v123
	ds_read_b128 v[24:27], v123 offset:64
	s_cmp_lt_u32 s62, 2
	s_cselect_b64 s[24:25], -1, 0
	s_lshl_b32 s30, s63, 2
	s_add_u32 s0, s2, s30
	s_waitcnt vmcnt(5) lgkmcnt(1)
	v_mfma_f32_16x16x32_bf16 v[20:23], v[20:23], v[56:59], 0
	s_addc_u32 s1, s3, 0
	s_and_b64 vcc, exec, s[24:25]
	ds_read_b128 v[132:135], v130 offset:64
	s_waitcnt vmcnt(4) lgkmcnt(1)
	v_mfma_f32_16x16x32_bf16 v[48:51], v[24:27], v[52:55], v[20:23]
	ds_read_b128 v[24:27], v124 offset:64
	s_nop 1
	ds_read_b128 v[20:23], v124
	s_waitcnt lgkmcnt(0)
	v_mfma_f32_16x16x32_bf16 v[20:23], v[20:23], v[56:59], 0
	s_nop 1
	v_cndmask_b32_e64 v67, v49, v238, s[6:7]
	v_mfma_f32_16x16x32_bf16 v[44:47], v[24:27], v[52:55], v[20:23]
	ds_read_b128 v[24:27], v125 offset:64
	s_nop 2
	ds_read_b128 v[20:23], v125
	s_waitcnt lgkmcnt(0)
	v_mfma_f32_16x16x32_bf16 v[20:23], v[20:23], v[56:59], 0
	v_mfma_f32_16x16x32_bf16 v[40:43], v[24:27], v[52:55], v[20:23]
	ds_read_b128 v[24:27], v126 offset:64
	s_nop 5
	ds_read_b128 v[20:23], v126
	s_waitcnt lgkmcnt(0)
	v_mfma_f32_16x16x32_bf16 v[20:23], v[20:23], v[56:59], 0
	v_mfma_f32_16x16x32_bf16 v[36:39], v[24:27], v[52:55], v[20:23]
	ds_read_b128 v[24:27], v127 offset:64
	s_nop 5
	ds_read_b128 v[20:23], v127
	s_waitcnt lgkmcnt(0)
	v_mfma_f32_16x16x32_bf16 v[20:23], v[20:23], v[56:59], 0
	v_mfma_f32_16x16x32_bf16 v[32:35], v[24:27], v[52:55], v[20:23]
	ds_read_b128 v[24:27], v128 offset:64
	s_nop 5
	ds_read_b128 v[20:23], v128
	s_waitcnt lgkmcnt(0)
	v_mfma_f32_16x16x32_bf16 v[20:23], v[20:23], v[56:59], 0
	v_mfma_f32_16x16x32_bf16 v[28:31], v[24:27], v[52:55], v[20:23]
	ds_read_b128 v[24:27], v129 offset:64
	s_nop 5
	ds_read_b128 v[20:23], v129
	s_waitcnt lgkmcnt(0)
	v_mfma_f32_16x16x32_bf16 v[20:23], v[20:23], v[56:59], 0
	v_mfma_f32_16x16x32_bf16 v[24:27], v[24:27], v[52:55], v[20:23]
	s_nop 6
	ds_read_b128 v[20:23], v130
	s_waitcnt lgkmcnt(0)
	v_mfma_f32_16x16x32_bf16 v[20:23], v[20:23], v[56:59], 0
	v_mfma_f32_16x16x32_bf16 v[20:23], v[132:135], v[52:55], v[20:23]
	ds_read_b128 v[132:135], v131
	s_waitcnt lgkmcnt(0)
	v_mfma_f32_16x16x32_bf16 v[56:59], v[132:135], v[56:59], 0
	ds_read_b128 v[132:135], v131 offset:64
	s_waitcnt lgkmcnt(0)
	v_mfma_f32_16x16x32_bf16 v[52:55], v[132:135], v[52:55], v[56:59]
	s_nop 4
	v_mov_b32_e32 v56, s30
	global_load_dword v247, v56, s[2:3] offset:4
	global_load_dword v248, v56, s[2:3] offset:8
	global_load_dword v56, v56, s[2:3]
	v_cndmask_b32_e64 v132, v238, v48, s[4:5]
	v_cndmask_b32_e64 v59, v238, v50, s[8:9]
	v_cndmask_b32_e64 v58, v238, v51, s[10:11]
	v_cndmask_b32_e64 v57, v52, v238, s[12:13]
	v_cndmask_b32_e64 v51, v238, v53, s[14:15]
	v_cndmask_b32_e64 v53, v54, v238, s[16:17]
	v_cndmask_b32_e64 v52, v55, v238, s[18:19]
	s_cbranch_vccz .LBB0_430
	v_readlane_b32 s62, v254, 48
	v_readlane_b32 s63, v254, 49
	v_cndmask_b32_e64 v30, v238, v30, s[66:67]
	v_cndmask_b32_e64 v31, v238, v31, s[68:69]
	v_cndmask_b32_e64 v132, v238, v132, s[62:63]
	v_readlane_b32 s62, v254, 53
	v_readlane_b32 s63, v254, 54
	v_cndmask_b32_e64 v24, v238, v24, s[70:71]
	v_cndmask_b32_e64 v25, v238, v25, s[72:73]
	v_cndmask_b32_e64 v67, v238, v67, s[62:63]
	v_readlane_b32 s62, v255, 4
	v_readlane_b32 s63, v255, 5
	v_cndmask_b32_e64 v26, v238, v26, s[74:75]
	v_cndmask_b32_e64 v27, v238, v27, s[76:77]
	v_cndmask_b32_e64 v59, v238, v59, s[62:63]
	v_readlane_b32 s62, v255, 6
	v_readlane_b32 s63, v255, 7
	v_cndmask_b32_e64 v20, v238, v20, s[78:79]
	v_cndmask_b32_e64 v21, v238, v21, s[80:81]
	v_cndmask_b32_e64 v58, v238, v58, s[62:63]
	v_readlane_b32 s62, v255, 8
	v_readlane_b32 s63, v255, 9
	v_cndmask_b32_e64 v22, v238, v22, s[82:83]
	v_cndmask_b32_e64 v23, v238, v23, s[26:27]
	v_cndmask_b32_e64 v44, v238, v44, s[62:63]
	v_readlane_b32 s62, v255, 10
	v_readlane_b32 s63, v255, 11
	v_cndmask_b32_e64 v57, v238, v57, s[28:29]
	v_cndmask_b32_e64 v51, v238, v51, s[52:53]
	v_cndmask_b32_e64 v45, v238, v45, s[62:63]
	v_readlane_b32 s62, v255, 12
	v_readlane_b32 s63, v255, 13
	v_cndmask_b32_e64 v53, v238, v53, s[54:55]
	v_cndmask_b32_e64 v52, v238, v52, s[56:57]
	v_cndmask_b32_e64 v46, v238, v46, s[62:63]
	v_readlane_b32 s62, v255, 14
	v_readlane_b32 s63, v255, 15
	s_nop 1
	v_cndmask_b32_e64 v47, v238, v47, s[62:63]
	v_readlane_b32 s62, v255, 16
	v_readlane_b32 s63, v255, 17
	s_nop 1
	v_cndmask_b32_e64 v40, v238, v40, s[62:63]
	v_readlane_b32 s62, v255, 18
	v_readlane_b32 s63, v255, 19
	s_nop 1
	v_cndmask_b32_e64 v41, v238, v41, s[62:63]
	v_readlane_b32 s62, v255, 20
	v_readlane_b32 s63, v255, 21
	s_nop 1
	v_cndmask_b32_e64 v42, v238, v42, s[62:63]
	v_readlane_b32 s62, v255, 22
	v_readlane_b32 s63, v255, 23
	s_nop 1
	v_cndmask_b32_e64 v43, v238, v43, s[62:63]
	v_readlane_b32 s62, v255, 24
	v_readlane_b32 s63, v255, 25
	s_nop 1
	v_cndmask_b32_e64 v36, v238, v36, s[62:63]
	v_readlane_b32 s62, v255, 26
	v_readlane_b32 s63, v255, 27
	s_nop 1
	v_cndmask_b32_e64 v37, v238, v37, s[62:63]
	v_readlane_b32 s62, v255, 28
	v_readlane_b32 s63, v255, 29
	s_nop 1
	v_cndmask_b32_e64 v38, v238, v38, s[62:63]
	v_readlane_b32 s62, v255, 30
	v_readlane_b32 s63, v255, 31
	s_nop 1
	v_cndmask_b32_e64 v39, v238, v39, s[62:63]
	v_readlane_b32 s62, v255, 32
	v_readlane_b32 s63, v255, 33
	s_nop 1
	v_cndmask_b32_e64 v32, v238, v32, s[62:63]
	v_readlane_b32 s62, v255, 34
	v_readlane_b32 s63, v255, 35
	s_nop 1
	v_cndmask_b32_e64 v33, v238, v33, s[62:63]
	v_readlane_b32 s62, v255, 36
	v_readlane_b32 s63, v255, 37
	s_nop 1
	v_cndmask_b32_e64 v34, v238, v34, s[62:63]
	v_readlane_b32 s62, v255, 38
	v_readlane_b32 s63, v255, 39
	s_nop 1
	v_cndmask_b32_e64 v35, v238, v35, s[62:63]
	v_readlane_b32 s62, v255, 40
	v_readlane_b32 s63, v255, 41
	s_nop 1
	v_cndmask_b32_e64 v28, v238, v28, s[62:63]
	v_readlane_b32 s62, v255, 42
	v_readlane_b32 s63, v255, 43
	s_nop 1
	v_cndmask_b32_e64 v29, v238, v29, s[62:63]
; #define GAS __attribute__((address_space(1)))
; __device__ __forceinline__ size_t PJ(int row, int col) { return ((size_t)(col >> 6) * SEQ + row) * 64 + (col & 63); }
; __device__ __forceinline__ void swa_item(LAS unsigned char* lds, const GAS bf16_t* proj, GAS bf16_t* mix, const GAS float* sinks, int nb, int hk, int tid, int w, int lane) {
;     ...
; #pragma unroll
;         for (int j = 0; j < 9; ++j)
; #pragma unroll
;             for (int i = 0; i < 4; ++i) mx = fmaxf(mx, s[j][i]);
;         mx = fmaxf(mx, __shfl_xor(mx, 16)); mx = fmaxf(mx, __shfl_xor(mx, 32));
;         float sum = 0.f; const float nmx = -mx * 1.4426950408889634f;
; #pragma unroll
;         for (int j = 0; j < 9; ++j)
; #pragma unroll
;             for (int i = 0; i < 4; ++i) { const float p = __builtin_amdgcn_exp2f(__builtin_fmaf(s[j][i], 1.4426950408889634f, nmx)); s[j][i] = p; sum += p; }
; __device__ __forceinline__ void conv_phase(const GAS bf16_t* proj, const GAS float* cw, const GAS float* cb_, GAS bf16_t* mix, int tid, int G, int bid) {
;     for (int it0 = bid * 512 + tid; it0 < (SEQ / 4) * 32; it0 += G * 512) {
;         const int it = (G == 256) ? (((512 * (bid & 7) + 16 * (bid >> 3)) << 5) + tid) : it0;
;         const int t0 = (it >> 5) * 4, c8 = (it & 31) * 8;
;         u32x4 ccr[6], cur[6], cbr[4];
; #pragma unroll
;         for (int r = 0; r < 6; ++r) { const int tt = t0 - 2 + r;
;             ccr[r] = (u32x4){0u, 0u, 0u, 0u}; cur[r] = (u32x4){0u, 0u, 0u, 0u};
;             if (tt >= 0) { ccr[r] = *(const GAS u32x4*)(proj + PJ(tt, C_CC + c8)); cur[r] = *(const GAS u32x4*)(proj + PJ(tt, C_CU + c8)); } }
.LBB0_430:
	v_ashrrev_i32_e32 v48, 8, v66
	v_ashrrev_i32_e32 v49, 31, v48
	v_lshlrev_b64 v[48:49], 12, v[48:49]
	s_movk_i32 s30, 0xff
	v_and_or_b32 v50, v66, s30, v48
	s_waitcnt vmcnt(0)
	v_readlane_b32 s98, v254, 47
	v_and_b32_e32 v242, 31, v0
	v_lshrrev_b32_e32 v246, 5, v0
	s_and_b32 s99, s98, 7
	s_lshr_b32 s98, s98, 3
	s_lshl_b32 s99, s99, 9
	s_lshl_b32 s98, s98, 4
	s_add_i32 s98, s98, s99
	v_add_u32_e32 v246, s98, v246
	v_lshlrev_b32_e32 v246, 2, v246
	v_lshlrev_b32_e32 v242, 3, v242
	v_lshrrev_b32_e32 v243, 6, v242
	v_and_b32_e32 v242, 63, v242
	v_lshlrev_b32_e32 v243, 21, v243
	v_lshl_add_u32 v242, v242, 1, v243
	v_lshl_add_u32 v242, v246, 7, v242
	v_add_u32_e32 v243, 0x4c00000, v242
	v_add_u32_e32 v244, 0x5400000, v242
	v_add_u32_e32 v245, 0x4400000, v242
	v_mov_b32_e32 v154, 0
	v_mov_b32_e32 v155, 0
	v_mov_b32_e32 v156, 0
	v_mov_b32_e32 v157, 0
	v_mov_b32_e32 v158, 0
	v_mov_b32_e32 v159, 0
	v_mov_b32_e32 v160, 0
	v_mov_b32_e32 v161, 0
	v_mov_b32_e32 v180, 0
	v_mov_b32_e32 v181, 0
	v_mov_b32_e32 v182, 0
	v_mov_b32_e32 v183, 0
	v_mov_b32_e32 v186, 0
	v_mov_b32_e32 v187, 0
	v_mov_b32_e32 v188, 0
	v_mov_b32_e32 v189, 0
	v_cmp_lt_u32_e64 s[100:101], 3, v246
	s_and_saveexec_b64 s[98:99], s[100:101]
	global_load_dwordx4 v[154:157], v243, s[94:95] offset:-256
	global_load_dwordx4 v[180:183], v244, s[94:95] offset:-256
	global_load_dwordx4 v[158:161], v243, s[94:95] offset:-128
	global_load_dwordx4 v[186:189], v244, s[94:95] offset:-128
	s_mov_b64 exec, s[98:99]
	global_load_dwordx4 v[162:165], v243, s[94:95]
	global_load_dwordx4 v[190:193], v244, s[94:95]
	global_load_dwordx4 v[166:169], v243, s[94:95] offset:128
	global_load_dwordx4 v[196:199], v244, s[94:95] offset:128
	global_load_dwordx4 v[170:173], v243, s[94:95] offset:256
	global_load_dwordx4 v[200:203], v244, s[94:95] offset:256
	global_load_dwordx4 v[174:177], v243, s[94:95] offset:384
	global_load_dwordx4 v[204:207], v244, s[94:95] offset:384
	global_load_dwordx4 v[208:211], v245, s[94:95]
	global_load_dwordx4 v[212:215], v245, s[94:95] offset:128
	global_load_dwordx4 v[216:219], v245, s[94:95] offset:256
	global_load_dwordx4 v[228:231], v245, s[94:95] offset:384
	v_max3_f32 v48, v56, v132, v67
	v_max3_f32 v48, v48, v59, v58
	v_max3_f32 v48, v48, v44, v45
	v_max3_f32 v48, v48, v46, v47
	v_max3_f32 v48, v48, v40, v41
	v_max3_f32 v48, v48, v42, v43
	v_max3_f32 v48, v48, v36, v37
	v_max3_f32 v48, v48, v38, v39
	v_max3_f32 v48, v48, v32, v33
	v_max3_f32 v48, v48, v34, v35
	v_max3_f32 v48, v48, v28, v29
	v_max3_f32 v48, v48, v30, v31
	v_max3_f32 v48, v48, v24, v25
	v_max3_f32 v48, v48, v26, v27
	v_max3_f32 v48, v48, v20, v21
	v_max3_f32 v48, v48, v22, v23
	v_max3_f32 v48, v48, v57, v51
	v_max3_f32 v48, v48, v53, v52
	ds_bpermute_b32 v54, v75, v48
	s_mul_i32 s30, s61, 0x300
	s_addk_i32 s30, 0x600
	s_andn2_b64 vcc, exec, s[24:25]
	s_waitcnt lgkmcnt(0)
	v_max_f32_e32 v54, v54, v54
	v_max_f32_e32 v48, v48, v54
	ds_bpermute_b32 v54, v76, v48
	s_waitcnt lgkmcnt(0)
	v_max_f32_e32 v54, v54, v54
	v_max_f32_e32 v48, v48, v54
	v_mul_f32_e32 v54, 0xbfb8aa3b, v48
	v_fmamk_f32 v55, v132, 0x3fb8aa3b, v54
	v_exp_f32_e32 v55, v55
	v_fmamk_f32 v67, v67, 0x3fb8aa3b, v54
	v_exp_f32_e32 v67, v67
	v_fmamk_f32 v59, v59, 0x3fb8aa3b, v54
	v_exp_f32_e32 v59, v59
	v_fmamk_f32 v58, v58, 0x3fb8aa3b, v54
	v_exp_f32_e32 v58, v58
	v_fmamk_f32 v44, v44, 0x3fb8aa3b, v54
	v_add_f32_e32 v66, 0, v55
	v_exp_f32_e32 v44, v44
	v_fmamk_f32 v45, v45, 0x3fb8aa3b, v54
	v_add_f32_e32 v66, v67, v66
	v_exp_f32_e32 v45, v45
	v_fmamk_f32 v46, v46, 0x3fb8aa3b, v54
	v_add_f32_e32 v66, v59, v66
	v_exp_f32_e32 v46, v46
	v_fmamk_f32 v47, v47, 0x3fb8aa3b, v54
	v_add_f32_e32 v66, v58, v66
	v_exp_f32_e32 v47, v47
	v_fmamk_f32 v40, v40, 0x3fb8aa3b, v54
	v_add_f32_e32 v66, v44, v66
	v_exp_f32_e32 v132, v40
	v_add_f32_e32 v66, v45, v66
	v_add_f32_e32 v66, v46, v66
	v_add_f32_e32 v66, v47, v66
	v_fmamk_f32 v41, v41, 0x3fb8aa3b, v54
	v_add_f32_e32 v40, v132, v66
	v_exp_f32_e32 v66, v41
	v_fmamk_f32 v41, v42, 0x3fb8aa3b, v54
	v_exp_f32_e32 v133, v41
	v_fmamk_f32 v41, v43, 0x3fb8aa3b, v54
	v_exp_f32_e32 v134, v41
	v_fmamk_f32 v36, v36, 0x3fb8aa3b, v54
	v_exp_f32_e32 v135, v36
	v_fmamk_f32 v37, v37, 0x3fb8aa3b, v54
	v_add_f32_e32 v40, v66, v40
	v_exp_f32_e32 v136, v37
	v_fmamk_f32 v37, v38, 0x3fb8aa3b, v54
	v_add_f32_e32 v40, v133, v40
	v_exp_f32_e32 v137, v37
	v_fmamk_f32 v37, v39, 0x3fb8aa3b, v54
	v_add_f32_e32 v40, v134, v40
	v_exp_f32_e32 v138, v37
	v_fmamk_f32 v32, v32, 0x3fb8aa3b, v54
	v_add_f32_e32 v36, v135, v40
	v_exp_f32_e32 v139, v32
	v_fmamk_f32 v33, v33, 0x3fb8aa3b, v54
	v_add_f32_e32 v36, v136, v36
	v_exp_f32_e32 v140, v33
	v_fmamk_f32 v33, v34, 0x3fb8aa3b, v54
	v_add_f32_e32 v36, v137, v36
	v_exp_f32_e32 v141, v33
	v_fmamk_f32 v33, v35, 0x3fb8aa3b, v54
	v_add_f32_e32 v36, v138, v36
	v_exp_f32_e32 v142, v33
	v_fmamk_f32 v28, v28, 0x3fb8aa3b, v54
	v_add_f32_e32 v32, v139, v36
	v_exp_f32_e32 v143, v28
	v_fmamk_f32 v29, v29, 0x3fb8aa3b, v54
	v_add_f32_e32 v32, v140, v32
	v_exp_f32_e32 v144, v29
	v_fmamk_f32 v29, v30, 0x3fb8aa3b, v54
	v_add_f32_e32 v32, v141, v32
	v_exp_f32_e32 v145, v29
	v_fmamk_f32 v29, v31, 0x3fb8aa3b, v54
	v_add_f32_e32 v32, v142, v32
	v_exp_f32_e32 v146, v29
	v_fmamk_f32 v24, v24, 0x3fb8aa3b, v54
	v_add_f32_e32 v28, v143, v32
	v_exp_f32_e32 v147, v24
	v_fmamk_f32 v25, v25, 0x3fb8aa3b, v54
	v_add_f32_e32 v28, v144, v28
	v_exp_f32_e32 v25, v25
	v_fmamk_f32 v26, v26, 0x3fb8aa3b, v54
	v_add_f32_e32 v28, v145, v28
	v_exp_f32_e32 v148, v26
	v_fmamk_f32 v26, v27, 0x3fb8aa3b, v54
	v_add_f32_e32 v28, v146, v28
	v_exp_f32_e32 v149, v26
	v_fmamk_f32 v20, v20, 0x3fb8aa3b, v54
	v_add_f32_e32 v24, v147, v28
	v_exp_f32_e32 v150, v20
	v_fmamk_f32 v21, v21, 0x3fb8aa3b, v54
	v_add_f32_e32 v24, v25, v24
	v_exp_f32_e32 v151, v21
	v_fmamk_f32 v21, v22, 0x3fb8aa3b, v54
	v_add_f32_e32 v24, v148, v24
	v_exp_f32_e32 v152, v21
	v_fmamk_f32 v21, v23, 0x3fb8aa3b, v54
	v_add_f32_e32 v24, v149, v24
	v_exp_f32_e32 v153, v21
	v_fmamk_f32 v21, v57, 0x3fb8aa3b, v54
	v_add_f32_e32 v20, v150, v24
	v_exp_f32_e32 v21, v21
	v_fmamk_f32 v22, v51, 0x3fb8aa3b, v54
	v_add_f32_e32 v20, v151, v20
	v_exp_f32_e32 v22, v22
	v_fmamk_f32 v23, v53, 0x3fb8aa3b, v54
	v_add_f32_e32 v20, v152, v20
	v_exp_f32_e32 v23, v23
	v_fmac_f32_e32 v54, 0x3fb8aa3b, v52
	v_add_f32_e32 v20, v153, v20
	v_exp_f32_e32 v24, v54
	v_add_f32_e32 v20, v21, v20
	v_add_f32_e32 v20, v22, v20
	v_add_f32_e32 v20, v23, v20
	v_add_f32_e32 v20, v24, v20
	ds_bpermute_b32 v26, v75, v20
	v_cndmask_b32_e64 v51, 0, 1, s[24:25]
	v_cmp_ne_u32_e64 s[96:97], 1, v51
	s_waitcnt lgkmcnt(0)
; __device__ __forceinline__ unsigned cvt_pk_bf16(float lo, float hi) { unsigned r; asm volatile("v_cvt_pk_bf16_f32 %0, %1, %2" : "=v"(r) : "v"(lo), "v"(hi)); return r; }
; #define LAS __attribute__((address_space(3)))
; #define GAS __attribute__((address_space(1)))
; __device__ __forceinline__ size_t TX(int row, int col) { return ((((size_t)(row >> 8) * 16 + (col >> 6)) * 256 + (row & 255)) << 6) + (col & 63); }
; __device__ __forceinline__ int tsw(int d) { return ((d >> 3) & 7) << 3; }
; #define MFMA16(a, b, c) __builtin_amdgcn_mfma_f32_16x16x32_bf16(a, b, c, 0, 0, 0)
; __device__ __forceinline__ void swa_item(LAS unsigned char* lds, const GAS bf16_t* proj, GAS bf16_t* mix, const GAS float* sinks, int nb, int hk, int tid, int w, int lane) {
;     ...
;         sum += __shfl_xor(sum, 16); sum += __shfl_xor(sum, 32);
;         const float inv = __builtin_amdgcn_rcpf(sum + __expf(sink - mx));
;         f32x4 o[4];
; #pragma unroll
;         for (int et = 0; et < 4; ++et) o[et] = (f32x4){0.f, 0.f, 0.f, 0.f};
; #pragma unroll
;         for (int jj = 0; jj < 5; ++jj) {
;             const int j0 = 2 * jj, j1 = 2 * jj + 1;
;             u32x2 plo, phi; plo.x = cvt_pk_bf16(s[j0][0], s[j0][1]); plo.y = cvt_pk_bf16(s[j0][2], s[j0][3]);
;             if (j1 < 9) { phi.x = cvt_pk_bf16(s[j1 < 9 ? j1 : 0][0], s[j1 < 9 ? j1 : 0][1]); phi.y = cvt_pk_bf16(s[j1 < 9 ? j1 : 0][2], s[j1 < 9 ? j1 : 0][3]); } else { phi.x = 0u; phi.y = 0u; }
;             const bf16x8 pb = mk8(plo, phi);
; #pragma unroll
;             for (int et = 0; et < 4; ++et) {
;                 const LAS bf16_t* vr = VTs + (16 * et + fr) * VS; const int sw = tsw(16 * et + fr), kc0 = 16 * (w + j0) + 4 * fq;
;                 const u32x2 a0 = *(const LAS u32x2*)(vr + (kc0 ^ sw)), a1 = *(const LAS u32x2*)(vr + ((kc0 + 16) ^ sw));
;                 o[et] = MFMA16(mk8(a0, a1), pb, o[et]);
;             }
;         }
; #pragma unroll
;         for (int et = 0; et < 4; ++et) { const f32x4 v = o[et] * inv; u32x2 wv; wv.x = cvt_pk_bf16(v[0], v[1]); wv.y = cvt_pk_bf16(v[2], v[3]);
;             *(GAS u32x2*)(mix + TX(tq, MIX_SWA + 64 * hq + 16 * et + 4 * fq)) = wv; }
;     }
;     __syncthreads();
	v_add_f32_e32 v20, v20, v26
	ds_bpermute_b32 v26, v76, v20
	s_waitcnt lgkmcnt(0)
	v_add_f32_e32 v20, v20, v26
	v_sub_f32_e32 v26, v56, v48
	v_mul_f32_e32 v26, 0x3fb8aa3b, v26
	v_exp_f32_e32 v26, v26
	v_or_b32_e32 v48, s30, v50
	v_add_f32_e32 v20, v26, v20
	v_cvt_pk_bf16_f32 v26, v55, v67
	v_cvt_pk_bf16_f32 v27, v59, v58
	v_cvt_pk_bf16_f32 v28, v44, v45
	v_cvt_pk_bf16_f32 v29, v46, v47
	ds_read_b64 v[30:31], v77 offset:36864
	ds_read_b64 v[32:33], v78 offset:36864
	ds_read_b64 v[34:35], v79 offset:36864
	ds_read_b64 v[36:37], v80 offset:36864
	ds_read_b64 v[38:39], v81 offset:36864
	ds_read_b64 v[40:41], v82 offset:36864
	ds_read_b64 v[42:43], v83 offset:36864
	ds_read_b64 v[44:45], v84 offset:36864
	s_waitcnt lgkmcnt(6)
	v_mfma_f32_16x16x32_bf16 v[30:33], v[30:33], v[26:29], 0
	v_rcp_f32_e32 v20, v20
	s_waitcnt lgkmcnt(4)
	v_mfma_f32_16x16x32_bf16 v[34:37], v[34:37], v[26:29], 0
	s_waitcnt lgkmcnt(2)
	v_mfma_f32_16x16x32_bf16 v[38:41], v[38:41], v[26:29], 0
	s_waitcnt lgkmcnt(0)
	v_mfma_f32_16x16x32_bf16 v[26:29], v[42:45], v[26:29], 0
	v_cvt_pk_bf16_f32 v42, v132, v66
	v_cvt_pk_bf16_f32 v43, v133, v134
	v_cvt_pk_bf16_f32 v44, v135, v136
	v_cvt_pk_bf16_f32 v45, v137, v138
	ds_read_b64 v[52:53], v85 offset:36864
	ds_read_b64 v[54:55], v86 offset:36864
	s_waitcnt lgkmcnt(0)
	v_mfma_f32_16x16x32_bf16 v[30:33], v[52:55], v[42:45], v[30:33]
	ds_read_b64 v[52:53], v87 offset:36864
	ds_read_b64 v[54:55], v88 offset:36864
	s_waitcnt lgkmcnt(0)
	v_mfma_f32_16x16x32_bf16 v[34:37], v[52:55], v[42:45], v[34:37]
	ds_read_b64 v[52:53], v89 offset:36864
	ds_read_b64 v[54:55], v90 offset:36864
	s_waitcnt lgkmcnt(0)
	v_mfma_f32_16x16x32_bf16 v[38:41], v[52:55], v[42:45], v[38:41]
	ds_read_b64 v[52:53], v91 offset:36864
	ds_read_b64 v[54:55], v92 offset:36864
	s_waitcnt lgkmcnt(0)
	v_mfma_f32_16x16x32_bf16 v[26:29], v[52:55], v[42:45], v[26:29]
	v_cvt_pk_bf16_f32 v42, v139, v140
	v_cvt_pk_bf16_f32 v43, v141, v142
	v_cvt_pk_bf16_f32 v44, v143, v144
	v_cvt_pk_bf16_f32 v45, v145, v146
	ds_read_b64 v[52:53], v93 offset:36864
	ds_read_b64 v[54:55], v94 offset:36864
	s_waitcnt lgkmcnt(0)
	v_mfma_f32_16x16x32_bf16 v[30:33], v[52:55], v[42:45], v[30:33]
	ds_read_b64 v[52:53], v95 offset:36864
	ds_read_b64 v[54:55], v96 offset:36864
	s_waitcnt lgkmcnt(0)
	v_mfma_f32_16x16x32_bf16 v[34:37], v[52:55], v[42:45], v[34:37]
	ds_read_b64 v[52:53], v97 offset:36864
	ds_read_b64 v[54:55], v98 offset:36864
	s_waitcnt lgkmcnt(0)
	v_mfma_f32_16x16x32_bf16 v[38:41], v[52:55], v[42:45], v[38:41]
	ds_read_b64 v[52:53], v99 offset:36864
	ds_read_b64 v[54:55], v100 offset:36864
	s_waitcnt lgkmcnt(0)
	v_mfma_f32_16x16x32_bf16 v[26:29], v[52:55], v[42:45], v[26:29]
	v_cvt_pk_bf16_f32 v42, v147, v25
	v_cvt_pk_bf16_f32 v43, v148, v149
	v_cvt_pk_bf16_f32 v44, v150, v151
	v_cvt_pk_bf16_f32 v45, v152, v153
	ds_read_b64 v[52:53], v101 offset:36864
	ds_read_b64 v[54:55], v102 offset:36864
	s_waitcnt lgkmcnt(0)
	v_mfma_f32_16x16x32_bf16 v[30:33], v[52:55], v[42:45], v[30:33]
	ds_read_b64 v[52:53], v103 offset:36864
	ds_read_b64 v[54:55], v104 offset:36864
	v_mov_b32_e32 v25, v179
	s_waitcnt lgkmcnt(0)
	v_mfma_f32_16x16x32_bf16 v[34:37], v[52:55], v[42:45], v[34:37]
	ds_read_b64 v[52:53], v105 offset:36864
	ds_read_b64 v[54:55], v106 offset:36864
	s_waitcnt lgkmcnt(0)
	v_mfma_f32_16x16x32_bf16 v[38:41], v[52:55], v[42:45], v[38:41]
	ds_read_b64 v[52:53], v107 offset:36864
	ds_read_b64 v[54:55], v108 offset:36864
	v_cvt_pk_bf16_f32 v22, v21, v22
	v_cvt_pk_bf16_f32 v23, v23, v24
	s_waitcnt lgkmcnt(0)
	v_mfma_f32_16x16x32_bf16 v[26:29], v[52:55], v[42:45], v[26:29]
	ds_read_b64 v[42:43], v109 offset:36864
	ds_read_b64 v[44:45], v110 offset:36864
	v_mov_b32_e32 v24, v179
	s_waitcnt lgkmcnt(0)
	s_nop 0
	v_mfma_f32_16x16x32_bf16 v[30:33], v[42:45], v[22:25], v[30:33]
	ds_read_b64 v[42:43], v111 offset:36864
	ds_read_b64 v[44:45], v112 offset:36864
	s_waitcnt lgkmcnt(0)
	v_mfma_f32_16x16x32_bf16 v[34:37], v[42:45], v[22:25], v[34:37]
	ds_read_b64 v[42:43], v113 offset:36864
	ds_read_b64 v[44:45], v114 offset:36864
	s_nop 1
	v_pk_mul_f32 v[30:31], v[30:31], v[20:21] op_sel_hi:[1,0]
	s_waitcnt lgkmcnt(0)
	v_mfma_f32_16x16x32_bf16 v[38:41], v[42:45], v[22:25], v[38:41]
	ds_read_b64 v[42:43], v115 offset:36864
	ds_read_b64 v[44:45], v116 offset:36864
	v_cvt_pk_bf16_f32 v30, v30, v31
	s_waitcnt lgkmcnt(0)
	v_mfma_f32_16x16x32_bf16 v[22:25], v[42:45], v[22:25], v[26:29]
	s_nop 2
	v_lshlrev_b64 v[26:27], 7, v[48:49]
	v_pk_mul_f32 v[28:29], v[32:33], v[20:21] op_sel_hi:[1,0]
	v_lshl_add_u64 v[26:27], v[64:65], 0, v[26:27]
	v_cvt_pk_bf16_f32 v31, v28, v29
	global_store_dwordx2 v[26:27], v[30:31], off
	v_pk_mul_f32 v[30:31], v[34:35], v[20:21] op_sel_hi:[1,0]
	v_pk_mul_f32 v[28:29], v[36:37], v[20:21] op_sel_hi:[1,0]
	v_cvt_pk_bf16_f32 v30, v30, v31
	v_pk_mul_f32 v[24:25], v[24:25], v[20:21] op_sel_hi:[1,0]
	v_cvt_pk_bf16_f32 v31, v28, v29
	global_store_dwordx2 v[26:27], v[30:31], off offset:32
	v_pk_mul_f32 v[28:29], v[40:41], v[20:21] op_sel_hi:[1,0]
	v_pk_mul_f32 v[30:31], v[38:39], v[20:21] op_sel_hi:[1,0]
	v_pk_mul_f32 v[20:21], v[22:23], v[20:21] op_sel_hi:[1,0]
	v_cvt_pk_bf16_f32 v30, v30, v31
	v_cvt_pk_bf16_f32 v31, v28, v29
	global_store_dwordx2 v[26:27], v[30:31], off offset:64
	v_cvt_pk_bf16_f32 v20, v20, v21
	v_cvt_pk_bf16_f32 v21, v24, v25
	global_store_dwordx2 v[26:27], v[20:21], off offset:96
	ds_read_b128 v[20:23], v123
	ds_read_b128 v[24:27], v123 offset:64
	s_waitcnt lgkmcnt(1)
	v_mfma_f32_16x16x32_bf16 v[20:23], v[20:23], v[16:19], 0
	ds_read_b128 v[56:59], v130 offset:64
	s_waitcnt lgkmcnt(1)
	v_mfma_f32_16x16x32_bf16 v[52:55], v[24:27], v[12:15], v[20:23]
	ds_read_b128 v[24:27], v124 offset:64
	s_nop 3
	ds_read_b128 v[20:23], v124
	s_waitcnt lgkmcnt(0)
; #define LAS __attribute__((address_space(3)))
; #define MFMA16(a, b, c) __builtin_amdgcn_mfma_f32_16x16x32_bf16(a, b, c, 0, 0, 0)
; __device__ __forceinline__ void swa_item(LAS unsigned char* lds, const GAS bf16_t* proj, GAS bf16_t* mix, const GAS float* sinks, int nb, int hk, int tid, int w, int lane) {
;     ...
;         for (int j = 0; j < 9; ++j) { s[j] = (f32x4){0.f, 0.f, 0.f, 0.f};
; #pragma unroll
;             for (int c = 0; c < 2; ++c) { const bf16x8 a = *(const LAS bf16x8*)(Ks + (16 * (w + j) + fr) * KS + 32 * c + 8 * fq); s[j] = MFMA16(a, qf[c], s[j]); } }
;         const float sink = sinks[hq];
;         float mx = sink;
; #pragma unroll
;         for (int j = 0; j < 9; ++j)
; #pragma unroll
;             for (int i = 0; i < 4; ++i) { const int kpos = 16 * (w + j) + 4 * fq + i;
;                 if (j == 0) s[j][i] = kpos > ql ? s[j][i] : -1e30f;
;                 if (j == 8) s[j][i] = kpos <= ql + 128 ? s[j][i] : -1e30f; }
;         if (nb == 0) {
; #pragma unroll
;             for (int j = 0; j < 9; ++j)
; #pragma unroll
;                 for (int i = 0; i < 4; ++i) s[j][i] = (16 * (w + j) + 4 * fq + i) >= 128 ? s[j][i] : -1e30f;
;         }
	v_mfma_f32_16x16x32_bf16 v[20:23], v[20:23], v[16:19], 0
	v_cndmask_b32_e64 v48, v53, v238, s[6:7]
	v_mfma_f32_16x16x32_bf16 v[44:47], v[24:27], v[12:15], v[20:23]
	ds_read_b128 v[24:27], v125 offset:64
	s_nop 4
	ds_read_b128 v[20:23], v125
	s_waitcnt lgkmcnt(0)
	v_mfma_f32_16x16x32_bf16 v[20:23], v[20:23], v[16:19], 0
	v_mfma_f32_16x16x32_bf16 v[40:43], v[24:27], v[12:15], v[20:23]
	ds_read_b128 v[24:27], v126 offset:64
	s_nop 5
	ds_read_b128 v[20:23], v126
	s_waitcnt lgkmcnt(0)
	v_mfma_f32_16x16x32_bf16 v[20:23], v[20:23], v[16:19], 0
	v_mfma_f32_16x16x32_bf16 v[36:39], v[24:27], v[12:15], v[20:23]
	ds_read_b128 v[24:27], v127 offset:64
	s_nop 5
	ds_read_b128 v[20:23], v127
	s_waitcnt lgkmcnt(0)
	v_mfma_f32_16x16x32_bf16 v[20:23], v[20:23], v[16:19], 0
	v_mfma_f32_16x16x32_bf16 v[32:35], v[24:27], v[12:15], v[20:23]
	ds_read_b128 v[24:27], v128 offset:64
	s_nop 5
	ds_read_b128 v[20:23], v128
	s_waitcnt lgkmcnt(0)
	v_mfma_f32_16x16x32_bf16 v[20:23], v[20:23], v[16:19], 0
	v_mfma_f32_16x16x32_bf16 v[28:31], v[24:27], v[12:15], v[20:23]
	ds_read_b128 v[24:27], v129 offset:64
	s_nop 5
	ds_read_b128 v[20:23], v129
	s_waitcnt lgkmcnt(0)
	v_mfma_f32_16x16x32_bf16 v[20:23], v[20:23], v[16:19], 0
	v_mfma_f32_16x16x32_bf16 v[20:23], v[24:27], v[12:15], v[20:23]
	ds_read_b128 v[24:27], v130
	s_waitcnt lgkmcnt(0)
	v_mfma_f32_16x16x32_bf16 v[24:27], v[24:27], v[16:19], 0
	v_mfma_f32_16x16x32_bf16 v[24:27], v[56:59], v[12:15], v[24:27]
	ds_read_b128 v[56:59], v131
	s_waitcnt lgkmcnt(0)
	v_mfma_f32_16x16x32_bf16 v[16:19], v[56:59], v[16:19], 0
	ds_read_b128 v[56:59], v131 offset:64
	s_waitcnt lgkmcnt(0)
	v_mfma_f32_16x16x32_bf16 v[56:59], v[56:59], v[12:15], v[16:19]
	v_mov_b32_e32 v12, v247
	s_nop 3
	v_cndmask_b32_e64 v17, v238, v52, s[4:5]
	v_cndmask_b32_e64 v19, v238, v54, s[8:9]
	v_cndmask_b32_e64 v18, v238, v55, s[10:11]
	v_cndmask_b32_e64 v16, v56, v238, s[12:13]
	v_cndmask_b32_e64 v15, v238, v57, s[14:15]
	v_cndmask_b32_e64 v14, v58, v238, s[16:17]
	v_cndmask_b32_e64 v13, v59, v238, s[18:19]
	s_cbranch_vccnz .LBB0_432
	v_readlane_b32 s24, v254, 48
	v_readlane_b32 s25, v254, 49
	v_cndmask_b32_e64 v30, v238, v30, s[66:67]
	v_cndmask_b32_e64 v31, v238, v31, s[68:69]
	v_cndmask_b32_e64 v17, v238, v17, s[24:25]
	v_readlane_b32 s24, v254, 53
	v_readlane_b32 s25, v254, 54
	v_cndmask_b32_e64 v20, v238, v20, s[70:71]
	v_cndmask_b32_e64 v21, v238, v21, s[72:73]
	v_cndmask_b32_e64 v48, v238, v48, s[24:25]
	v_readlane_b32 s24, v255, 4
	v_readlane_b32 s25, v255, 5
	v_cndmask_b32_e64 v22, v238, v22, s[74:75]
	v_cndmask_b32_e64 v23, v238, v23, s[76:77]
	v_cndmask_b32_e64 v19, v238, v19, s[24:25]
	v_readlane_b32 s24, v255, 6
	v_readlane_b32 s25, v255, 7
	v_cndmask_b32_e64 v24, v238, v24, s[78:79]
	v_cndmask_b32_e64 v25, v238, v25, s[80:81]
	v_cndmask_b32_e64 v18, v238, v18, s[24:25]
	v_readlane_b32 s24, v255, 8
	v_readlane_b32 s25, v255, 9
	v_cndmask_b32_e64 v26, v238, v26, s[82:83]
	v_cndmask_b32_e64 v27, v238, v27, s[26:27]
	v_cndmask_b32_e64 v44, v238, v44, s[24:25]
	v_readlane_b32 s24, v255, 10
	v_readlane_b32 s25, v255, 11
	v_cndmask_b32_e64 v16, v238, v16, s[28:29]
	v_cndmask_b32_e64 v15, v238, v15, s[52:53]
	v_cndmask_b32_e64 v45, v238, v45, s[24:25]
	v_readlane_b32 s24, v255, 12
	v_readlane_b32 s25, v255, 13
	v_cndmask_b32_e64 v14, v238, v14, s[54:55]
	v_cndmask_b32_e64 v13, v238, v13, s[56:57]
	v_cndmask_b32_e64 v46, v238, v46, s[24:25]
	v_readlane_b32 s24, v255, 14
	v_readlane_b32 s25, v255, 15
	s_nop 1
	v_cndmask_b32_e64 v47, v238, v47, s[24:25]
	v_readlane_b32 s24, v255, 16
	v_readlane_b32 s25, v255, 17
	s_nop 1
	v_cndmask_b32_e64 v40, v238, v40, s[24:25]
	v_readlane_b32 s24, v255, 18
	v_readlane_b32 s25, v255, 19
	s_nop 1
	v_cndmask_b32_e64 v41, v238, v41, s[24:25]
	v_readlane_b32 s24, v255, 20
	v_readlane_b32 s25, v255, 21
	s_nop 1
	v_cndmask_b32_e64 v42, v238, v42, s[24:25]
	v_readlane_b32 s24, v255, 22
	v_readlane_b32 s25, v255, 23
	s_nop 1
	v_cndmask_b32_e64 v43, v238, v43, s[24:25]
	v_readlane_b32 s24, v255, 24
	v_readlane_b32 s25, v255, 25
	s_nop 1
	v_cndmask_b32_e64 v36, v238, v36, s[24:25]
	v_readlane_b32 s24, v255, 26
	v_readlane_b32 s25, v255, 27
	s_nop 1
	v_cndmask_b32_e64 v37, v238, v37, s[24:25]
	v_readlane_b32 s24, v255, 28
	v_readlane_b32 s25, v255, 29
	s_nop 1
	v_cndmask_b32_e64 v38, v238, v38, s[24:25]
	v_readlane_b32 s24, v255, 30
	v_readlane_b32 s25, v255, 31
	s_nop 1
	v_cndmask_b32_e64 v39, v238, v39, s[24:25]
	v_readlane_b32 s24, v255, 32
	v_readlane_b32 s25, v255, 33
	s_nop 1
	v_cndmask_b32_e64 v32, v238, v32, s[24:25]
	v_readlane_b32 s24, v255, 34
	v_readlane_b32 s25, v255, 35
	s_nop 1
	v_cndmask_b32_e64 v33, v238, v33, s[24:25]
	v_readlane_b32 s24, v255, 36
	v_readlane_b32 s25, v255, 37
	s_nop 1
	v_cndmask_b32_e64 v34, v238, v34, s[24:25]
	v_readlane_b32 s24, v255, 38
	v_readlane_b32 s25, v255, 39
	s_nop 1
	v_cndmask_b32_e64 v35, v238, v35, s[24:25]
	v_readlane_b32 s24, v255, 40
	v_readlane_b32 s25, v255, 41
	s_nop 1
	v_cndmask_b32_e64 v28, v238, v28, s[24:25]
	v_readlane_b32 s24, v255, 42
	v_readlane_b32 s25, v255, 43
	s_nop 1
	v_cndmask_b32_e64 v29, v238, v29, s[24:25]
; __device__ __forceinline__ void swa_item(LAS unsigned char* lds, const GAS bf16_t* proj, GAS bf16_t* mix, const GAS float* sinks, int nb, int hk, int tid, int w, int lane) {
;     ...
; #pragma unroll
;         for (int j = 0; j < 9; ++j)
; #pragma unroll
;             for (int i = 0; i < 4; ++i) mx = fmaxf(mx, s[j][i]);
;         mx = fmaxf(mx, __shfl_xor(mx, 16)); mx = fmaxf(mx, __shfl_xor(mx, 32));
;         float sum = 0.f; const float nmx = -mx * 1.4426950408889634f;
; #pragma unroll
;         for (int j = 0; j < 9; ++j)
; #pragma unroll
;             for (int i = 0; i < 4; ++i) { const float p = __builtin_amdgcn_exp2f(__builtin_fmaf(s[j][i], 1.4426950408889634f, nmx)); s[j][i] = p; sum += p; }
;         sum += __shfl_xor(sum, 16); sum += __shfl_xor(sum, 32);
;         const float inv = __builtin_amdgcn_rcpf(sum + __expf(sink - mx));
;         f32x4 o[4];
; #pragma unroll
;         for (int et = 0; et < 4; ++et) o[et] = (f32x4){0.f, 0.f, 0.f, 0.f};
.LBB0_432:
	s_nop 0
	v_max3_f32 v51, v12, v17, v48
	v_max3_f32 v51, v51, v19, v18
	v_max3_f32 v51, v51, v44, v45
	v_max3_f32 v51, v51, v46, v47
	v_max3_f32 v51, v51, v40, v41
	v_max3_f32 v51, v51, v42, v43
	v_max3_f32 v51, v51, v36, v37
	v_max3_f32 v51, v51, v38, v39
	v_max3_f32 v51, v51, v32, v33
	v_max3_f32 v51, v51, v34, v35
	v_max3_f32 v51, v51, v28, v29
	v_max3_f32 v51, v51, v30, v31
	v_max3_f32 v51, v51, v20, v21
	v_max3_f32 v51, v51, v22, v23
	v_max3_f32 v51, v51, v24, v25
	v_max3_f32 v51, v51, v26, v27
	v_max3_f32 v51, v51, v16, v15
	v_max3_f32 v51, v51, v14, v13
	ds_bpermute_b32 v52, v75, v51
	s_lshl_b32 s24, s60, 8
	s_addk_i32 s24, 0x600
	s_and_b64 vcc, exec, s[96:97]
	s_waitcnt lgkmcnt(0)
	v_max_f32_e32 v52, v52, v52
	v_max_f32_e32 v51, v51, v52
	ds_bpermute_b32 v52, v76, v51
	s_waitcnt lgkmcnt(0)
	v_max_f32_e32 v52, v52, v52
	v_max_f32_e32 v51, v51, v52
	v_mul_f32_e32 v52, 0xbfb8aa3b, v51
	v_fmamk_f32 v17, v17, 0x3fb8aa3b, v52
	v_exp_f32_e32 v17, v17
	v_fmamk_f32 v48, v48, 0x3fb8aa3b, v52
	v_exp_f32_e32 v48, v48
	v_fmamk_f32 v19, v19, 0x3fb8aa3b, v52
	v_exp_f32_e32 v19, v19
	v_fmamk_f32 v18, v18, 0x3fb8aa3b, v52
	v_exp_f32_e32 v54, v18
	v_fmamk_f32 v44, v44, 0x3fb8aa3b, v52
	v_add_f32_e32 v53, 0, v17
	v_exp_f32_e32 v44, v44
	v_fmamk_f32 v45, v45, 0x3fb8aa3b, v52
	v_add_f32_e32 v53, v48, v53
	v_exp_f32_e32 v45, v45
	v_fmamk_f32 v46, v46, 0x3fb8aa3b, v52
	v_add_f32_e32 v53, v19, v53
	v_exp_f32_e32 v46, v46
	v_fmamk_f32 v47, v47, 0x3fb8aa3b, v52
	v_add_f32_e32 v18, v54, v53
	v_exp_f32_e32 v47, v47
	v_fmamk_f32 v40, v40, 0x3fb8aa3b, v52
	v_add_f32_e32 v18, v44, v18
	v_exp_f32_e32 v40, v40
	v_fmamk_f32 v41, v41, 0x3fb8aa3b, v52
	v_add_f32_e32 v18, v45, v18
	v_exp_f32_e32 v41, v41
	v_fmamk_f32 v42, v42, 0x3fb8aa3b, v52
	v_add_f32_e32 v18, v46, v18
	v_exp_f32_e32 v42, v42
	v_fmamk_f32 v43, v43, 0x3fb8aa3b, v52
	v_add_f32_e32 v18, v47, v18
	v_exp_f32_e32 v43, v43
	v_fmamk_f32 v36, v36, 0x3fb8aa3b, v52
	v_add_f32_e32 v18, v40, v18
	v_exp_f32_e32 v53, v36
	v_fmamk_f32 v36, v37, 0x3fb8aa3b, v52
	v_add_f32_e32 v18, v41, v18
	v_exp_f32_e32 v55, v36
	v_fmamk_f32 v36, v38, 0x3fb8aa3b, v52
	v_add_f32_e32 v18, v42, v18
	v_exp_f32_e32 v38, v36
	v_fmamk_f32 v36, v39, 0x3fb8aa3b, v52
	v_add_f32_e32 v18, v43, v18
	v_exp_f32_e32 v39, v36
	v_fmamk_f32 v32, v32, 0x3fb8aa3b, v52
	v_add_f32_e32 v18, v53, v18
	v_exp_f32_e32 v56, v32
	v_fmamk_f32 v32, v33, 0x3fb8aa3b, v52
	v_add_f32_e32 v18, v55, v18
	v_exp_f32_e32 v57, v32
	v_fmamk_f32 v32, v34, 0x3fb8aa3b, v52
	v_add_f32_e32 v18, v38, v18
	v_exp_f32_e32 v58, v32
	v_fmamk_f32 v32, v35, 0x3fb8aa3b, v52
	v_add_f32_e32 v18, v39, v18
	v_exp_f32_e32 v59, v32
	v_fmamk_f32 v28, v28, 0x3fb8aa3b, v52
	v_add_f32_e32 v18, v56, v18
	v_exp_f32_e32 v66, v28
	v_fmamk_f32 v28, v29, 0x3fb8aa3b, v52
	v_add_f32_e32 v18, v57, v18
	v_exp_f32_e32 v67, v28
	v_fmamk_f32 v28, v30, 0x3fb8aa3b, v52
	v_add_f32_e32 v18, v58, v18
	v_exp_f32_e32 v132, v28
	v_fmamk_f32 v28, v31, 0x3fb8aa3b, v52
	v_add_f32_e32 v18, v59, v18
	v_exp_f32_e32 v133, v28
	v_fmamk_f32 v20, v20, 0x3fb8aa3b, v52
	v_add_f32_e32 v18, v66, v18
	v_exp_f32_e32 v134, v20
	v_fmamk_f32 v20, v21, 0x3fb8aa3b, v52
	v_add_f32_e32 v18, v67, v18
	v_exp_f32_e32 v135, v20
	v_fmamk_f32 v20, v22, 0x3fb8aa3b, v52
	v_add_f32_e32 v18, v132, v18
	v_exp_f32_e32 v136, v20
	v_fmamk_f32 v20, v23, 0x3fb8aa3b, v52
	v_add_f32_e32 v18, v133, v18
	v_exp_f32_e32 v137, v20
	v_fmamk_f32 v20, v24, 0x3fb8aa3b, v52
	v_add_f32_e32 v18, v134, v18
	v_exp_f32_e32 v138, v20
	v_fmamk_f32 v20, v25, 0x3fb8aa3b, v52
	v_add_f32_e32 v18, v135, v18
	v_exp_f32_e32 v139, v20
	v_fmamk_f32 v20, v26, 0x3fb8aa3b, v52
	v_add_f32_e32 v18, v136, v18
	v_exp_f32_e32 v140, v20
	v_fmamk_f32 v20, v27, 0x3fb8aa3b, v52
	v_add_f32_e32 v18, v137, v18
	v_exp_f32_e32 v141, v20
	v_fmamk_f32 v16, v16, 0x3fb8aa3b, v52
	v_add_f32_e32 v18, v138, v18
	v_exp_f32_e32 v16, v16
	v_fmamk_f32 v15, v15, 0x3fb8aa3b, v52
	v_add_f32_e32 v18, v139, v18
	v_exp_f32_e32 v15, v15
	v_fmamk_f32 v14, v14, 0x3fb8aa3b, v52
	v_add_f32_e32 v18, v140, v18
	v_exp_f32_e32 v14, v14
	v_fmac_f32_e32 v52, 0x3fb8aa3b, v13
	v_add_f32_e32 v18, v141, v18
	v_exp_f32_e32 v13, v52
	v_add_f32_e32 v18, v16, v18
	v_add_f32_e32 v18, v15, v18
	v_add_f32_e32 v18, v14, v18
	v_add_f32_e32 v18, v13, v18
	ds_bpermute_b32 v20, v75, v18
	v_sub_f32_e32 v12, v12, v51
	v_mul_f32_e32 v12, 0x3fb8aa3b, v12
	v_exp_f32_e32 v12, v12
	s_waitcnt lgkmcnt(0)
	v_add_f32_e32 v18, v18, v20
	ds_bpermute_b32 v20, v76, v18
	s_waitcnt lgkmcnt(0)
	v_add_f32_e32 v18, v18, v20
	v_add_f32_e32 v12, v12, v18
	v_cvt_pk_bf16_f32 v18, v17, v48
	v_cvt_pk_bf16_f32 v19, v19, v54
	v_cvt_pk_bf16_f32 v20, v44, v45
	v_cvt_pk_bf16_f32 v21, v46, v47
	ds_read_b64 v[22:23], v77 offset:36864
	ds_read_b64 v[24:25], v78 offset:36864
	ds_read_b64 v[26:27], v79 offset:36864
	ds_read_b64 v[28:29], v80 offset:36864
	ds_read_b64 v[30:31], v81 offset:36864
	ds_read_b64 v[32:33], v82 offset:36864
	ds_read_b64 v[34:35], v83 offset:36864
	ds_read_b64 v[36:37], v84 offset:36864
	s_waitcnt lgkmcnt(6)
	v_mfma_f32_16x16x32_bf16 v[22:25], v[22:25], v[18:21], 0
	v_rcp_f32_e32 v12, v12
	v_or_b32_e32 v48, s24, v50
	s_waitcnt lgkmcnt(4)
	v_mfma_f32_16x16x32_bf16 v[26:29], v[26:29], v[18:21], 0
	s_waitcnt lgkmcnt(2)
	v_mfma_f32_16x16x32_bf16 v[30:33], v[30:33], v[18:21], 0
	s_waitcnt lgkmcnt(0)
	v_mfma_f32_16x16x32_bf16 v[18:21], v[34:37], v[18:21], 0
	v_cvt_pk_bf16_f32 v34, v40, v41
	v_cvt_pk_bf16_f32 v35, v42, v43
	v_cvt_pk_bf16_f32 v36, v53, v55
	v_cvt_pk_bf16_f32 v37, v38, v39
	ds_read_b64 v[38:39], v85 offset:36864
	ds_read_b64 v[40:41], v86 offset:36864
	s_waitcnt lgkmcnt(0)
; __device__ __forceinline__ unsigned cvt_pk_bf16(float lo, float hi) { unsigned r; asm volatile("v_cvt_pk_bf16_f32 %0, %1, %2" : "=v"(r) : "v"(lo), "v"(hi)); return r; }
; #define LAS __attribute__((address_space(3)))
; #define GAS __attribute__((address_space(1)))
; __device__ __forceinline__ size_t TX(int row, int col) { return ((((size_t)(row >> 8) * 16 + (col >> 6)) * 256 + (row & 255)) << 6) + (col & 63); }
; __device__ __forceinline__ int tsw(int d) { return ((d >> 3) & 7) << 3; }
; #define MFMA16(a, b, c) __builtin_amdgcn_mfma_f32_16x16x32_bf16(a, b, c, 0, 0, 0)
; __device__ __forceinline__ void swa_item(LAS unsigned char* lds, const GAS bf16_t* proj, GAS bf16_t* mix, const GAS float* sinks, int nb, int hk, int tid, int w, int lane) {
;     ...
;         for (int j = 0; j < 9; ++j) { s[j] = (f32x4){0.f, 0.f, 0.f, 0.f};
; #pragma unroll
;             for (int c = 0; c < 2; ++c) { const bf16x8 a = *(const LAS bf16x8*)(Ks + (16 * (w + j) + fr) * KS + 32 * c + 8 * fq); s[j] = MFMA16(a, qf[c], s[j]); } }
;         const float sink = sinks[hq];
;     ...
; #pragma unroll
;         for (int jj = 0; jj < 5; ++jj) {
;             const int j0 = 2 * jj, j1 = 2 * jj + 1;
;             u32x2 plo, phi; plo.x = cvt_pk_bf16(s[j0][0], s[j0][1]); plo.y = cvt_pk_bf16(s[j0][2], s[j0][3]);
;             if (j1 < 9) { phi.x = cvt_pk_bf16(s[j1 < 9 ? j1 : 0][0], s[j1 < 9 ? j1 : 0][1]); phi.y = cvt_pk_bf16(s[j1 < 9 ? j1 : 0][2], s[j1 < 9 ? j1 : 0][3]); } else { phi.x = 0u; phi.y = 0u; }
;             const bf16x8 pb = mk8(plo, phi);
; #pragma unroll
;             for (int et = 0; et < 4; ++et) {
;                 const LAS bf16_t* vr = VTs + (16 * et + fr) * VS; const int sw = tsw(16 * et + fr), kc0 = 16 * (w + j0) + 4 * fq;
;                 const u32x2 a0 = *(const LAS u32x2*)(vr + (kc0 ^ sw)), a1 = *(const LAS u32x2*)(vr + ((kc0 + 16) ^ sw));
;                 o[et] = MFMA16(mk8(a0, a1), pb, o[et]);
;             }
;         }
; #pragma unroll
;         for (int et = 0; et < 4; ++et) { const f32x4 v = o[et] * inv; u32x2 wv; wv.x = cvt_pk_bf16(v[0], v[1]); wv.y = cvt_pk_bf16(v[2], v[3]);
;             *(GAS u32x2*)(mix + TX(tq, MIX_SWA + 64 * hq + 16 * et + 4 * fq)) = wv; }
	v_mfma_f32_16x16x32_bf16 v[22:25], v[38:41], v[34:37], v[22:25]
	ds_read_b64 v[38:39], v87 offset:36864
	ds_read_b64 v[40:41], v88 offset:36864
	s_waitcnt lgkmcnt(0)
	v_mfma_f32_16x16x32_bf16 v[26:29], v[38:41], v[34:37], v[26:29]
	ds_read_b64 v[38:39], v89 offset:36864
	ds_read_b64 v[40:41], v90 offset:36864
	s_waitcnt lgkmcnt(0)
	v_mfma_f32_16x16x32_bf16 v[30:33], v[38:41], v[34:37], v[30:33]
	ds_read_b64 v[38:39], v91 offset:36864
	ds_read_b64 v[40:41], v92 offset:36864
	s_waitcnt lgkmcnt(0)
	v_mfma_f32_16x16x32_bf16 v[18:21], v[38:41], v[34:37], v[18:21]
	v_cvt_pk_bf16_f32 v34, v56, v57
	v_cvt_pk_bf16_f32 v35, v58, v59
	v_cvt_pk_bf16_f32 v36, v66, v67
	v_cvt_pk_bf16_f32 v37, v132, v133
	ds_read_b64 v[38:39], v93 offset:36864
	ds_read_b64 v[40:41], v94 offset:36864
	s_waitcnt lgkmcnt(0)
	v_mfma_f32_16x16x32_bf16 v[22:25], v[38:41], v[34:37], v[22:25]
	ds_read_b64 v[38:39], v95 offset:36864
	ds_read_b64 v[40:41], v96 offset:36864
	s_waitcnt lgkmcnt(0)
	v_mfma_f32_16x16x32_bf16 v[26:29], v[38:41], v[34:37], v[26:29]
	ds_read_b64 v[38:39], v97 offset:36864
	ds_read_b64 v[40:41], v98 offset:36864
	s_waitcnt lgkmcnt(0)
	v_mfma_f32_16x16x32_bf16 v[30:33], v[38:41], v[34:37], v[30:33]
	ds_read_b64 v[38:39], v99 offset:36864
	ds_read_b64 v[40:41], v100 offset:36864
	s_waitcnt lgkmcnt(0)
	v_mfma_f32_16x16x32_bf16 v[18:21], v[38:41], v[34:37], v[18:21]
	v_cvt_pk_bf16_f32 v34, v134, v135
	v_cvt_pk_bf16_f32 v35, v136, v137
	v_cvt_pk_bf16_f32 v36, v138, v139
	v_cvt_pk_bf16_f32 v37, v140, v141
	ds_read_b64 v[38:39], v101 offset:36864
	ds_read_b64 v[40:41], v102 offset:36864
	s_waitcnt lgkmcnt(0)
	v_mfma_f32_16x16x32_bf16 v[22:25], v[38:41], v[34:37], v[22:25]
	ds_read_b64 v[38:39], v103 offset:36864
	ds_read_b64 v[40:41], v104 offset:36864
	s_waitcnt lgkmcnt(0)
	v_mfma_f32_16x16x32_bf16 v[26:29], v[38:41], v[34:37], v[26:29]
	ds_read_b64 v[38:39], v105 offset:36864
	ds_read_b64 v[40:41], v106 offset:36864
	s_waitcnt lgkmcnt(0)
	v_mfma_f32_16x16x32_bf16 v[30:33], v[38:41], v[34:37], v[30:33]
	ds_read_b64 v[38:39], v107 offset:36864
	ds_read_b64 v[40:41], v108 offset:36864
	s_waitcnt lgkmcnt(0)
	v_mfma_f32_16x16x32_bf16 v[18:21], v[38:41], v[34:37], v[18:21]
	v_cvt_pk_bf16_f32 v34, v16, v15
	v_cvt_pk_bf16_f32 v35, v14, v13
	ds_read_b64 v[16:17], v116 offset:36864
	ds_read_b64 v[14:15], v115 offset:36864
	ds_read_b64 v[40:41], v114 offset:36864
	ds_read_b64 v[38:39], v113 offset:36864
	ds_read_b64 v[44:45], v112 offset:36864
	ds_read_b64 v[42:43], v111 offset:36864
	ds_read_b64 v[54:55], v110 offset:36864
	ds_read_b64 v[52:53], v109 offset:36864
	v_mov_b32_e32 v36, v179
	v_mov_b32_e32 v37, v179
	s_waitcnt lgkmcnt(0)
	s_nop 0
	v_mfma_f32_16x16x32_bf16 v[22:25], v[52:55], v[34:37], v[22:25]
	v_mfma_f32_16x16x32_bf16 v[26:29], v[42:45], v[34:37], v[26:29]
	v_mfma_f32_16x16x32_bf16 v[30:33], v[38:41], v[34:37], v[30:33]
	s_nop 5
	v_mul_f32_e64 v22, v22, v12
	v_mul_f32_e64 v23, v23, v12
	v_cvt_pk_bf16_f32 v22, v22, v23
	v_mfma_f32_16x16x32_bf16 v[14:17], v[14:17], v[34:37], v[18:21]
	s_nop 2
	v_lshlrev_b64 v[18:19], 7, v[48:49]
	v_pk_mul_f32 v[20:21], v[24:25], v[12:13] op_sel_hi:[1,0]
	v_lshl_add_u64 v[18:19], v[64:65], 0, v[18:19]
	v_cvt_pk_bf16_f32 v23, v20, v21
	global_store_dwordx2 v[18:19], v[22:23], off
	v_pk_mul_f32 v[22:23], v[26:27], v[12:13] op_sel_hi:[1,0]
	v_pk_mul_f32 v[20:21], v[28:29], v[12:13] op_sel_hi:[1,0]
	v_cvt_pk_bf16_f32 v22, v22, v23
	v_pk_mul_f32 v[16:17], v[16:17], v[12:13] op_sel_hi:[1,0]
	v_cvt_pk_bf16_f32 v23, v20, v21
	global_store_dwordx2 v[18:19], v[22:23], off offset:32
	v_pk_mul_f32 v[20:21], v[32:33], v[12:13] op_sel_hi:[1,0]
	v_pk_mul_f32 v[22:23], v[30:31], v[12:13] op_sel_hi:[1,0]
	v_pk_mul_f32 v[12:13], v[14:15], v[12:13] op_sel_hi:[1,0]
	v_cvt_pk_bf16_f32 v22, v22, v23
	v_cvt_pk_bf16_f32 v23, v20, v21
	global_store_dwordx2 v[18:19], v[22:23], off offset:64
	v_cvt_pk_bf16_f32 v12, v12, v13
	v_cvt_pk_bf16_f32 v13, v16, v17
	global_store_dwordx2 v[18:19], v[12:13], off offset:96
	ds_read_b128 v[12:15], v123
	ds_read_b128 v[16:19], v123 offset:64
	s_waitcnt lgkmcnt(1)
	v_mfma_f32_16x16x32_bf16 v[12:15], v[12:15], v[8:11], 0
	ds_read_b128 v[52:55], v130 offset:64
	s_waitcnt lgkmcnt(1)
	v_mfma_f32_16x16x32_bf16 v[42:45], v[16:19], v[4:7], v[12:15]
	ds_read_b128 v[16:19], v124 offset:64
	s_nop 3
	ds_read_b128 v[12:15], v124
	s_waitcnt lgkmcnt(0)
	v_mfma_f32_16x16x32_bf16 v[12:15], v[12:15], v[8:11], 0
	v_cndmask_b32_e64 v41, v238, v42, s[4:5]
	v_cndmask_b32_e64 v40, v43, v238, s[6:7]
	v_mfma_f32_16x16x32_bf16 v[36:39], v[16:19], v[4:7], v[12:15]
	ds_read_b128 v[16:19], v125 offset:64
	s_nop 3
	ds_read_b128 v[12:15], v125
	s_waitcnt lgkmcnt(0)
	v_mfma_f32_16x16x32_bf16 v[12:15], v[12:15], v[8:11], 0
	v_mfma_f32_16x16x32_bf16 v[32:35], v[16:19], v[4:7], v[12:15]
	ds_read_b128 v[16:19], v126 offset:64
	s_nop 5
	ds_read_b128 v[12:15], v126
	s_waitcnt lgkmcnt(0)
	v_mfma_f32_16x16x32_bf16 v[12:15], v[12:15], v[8:11], 0
	v_mfma_f32_16x16x32_bf16 v[28:31], v[16:19], v[4:7], v[12:15]
	ds_read_b128 v[16:19], v127 offset:64
	s_nop 5
	ds_read_b128 v[12:15], v127
	s_waitcnt lgkmcnt(0)
	v_mfma_f32_16x16x32_bf16 v[12:15], v[12:15], v[8:11], 0
	v_mfma_f32_16x16x32_bf16 v[24:27], v[16:19], v[4:7], v[12:15]
	ds_read_b128 v[16:19], v128 offset:64
	s_nop 5
	ds_read_b128 v[12:15], v128
	s_waitcnt lgkmcnt(0)
	v_mfma_f32_16x16x32_bf16 v[12:15], v[12:15], v[8:11], 0
	v_mfma_f32_16x16x32_bf16 v[20:23], v[16:19], v[4:7], v[12:15]
	ds_read_b128 v[16:19], v129 offset:64
	s_nop 5
	ds_read_b128 v[12:15], v129
	s_waitcnt lgkmcnt(0)
	v_mfma_f32_16x16x32_bf16 v[12:15], v[12:15], v[8:11], 0
	v_mfma_f32_16x16x32_bf16 v[12:15], v[16:19], v[4:7], v[12:15]
	ds_read_b128 v[16:19], v130
	s_waitcnt lgkmcnt(0)
	v_mfma_f32_16x16x32_bf16 v[16:19], v[16:19], v[8:11], 0
	v_mfma_f32_16x16x32_bf16 v[16:19], v[52:55], v[4:7], v[16:19]
	ds_read_b128 v[52:55], v131
	s_waitcnt lgkmcnt(0)
	v_mfma_f32_16x16x32_bf16 v[8:11], v[52:55], v[8:11], 0
	ds_read_b128 v[52:55], v131 offset:64
	s_waitcnt lgkmcnt(0)
	v_mfma_f32_16x16x32_bf16 v[52:55], v[52:55], v[4:7], v[8:11]
	v_mov_b32_e32 v4, v248
	s_nop 3
	v_cndmask_b32_e64 v11, v238, v44, s[8:9]
	v_cndmask_b32_e64 v10, v238, v45, s[10:11]
	s_nop 0
	v_cndmask_b32_e64 v9, v52, v238, s[12:13]
	v_cndmask_b32_e64 v8, v238, v53, s[14:15]
	v_cndmask_b32_e64 v7, v54, v238, s[16:17]
	v_cndmask_b32_e64 v6, v55, v238, s[18:19]
	s_cbranch_vccnz .LBB0_411
; __device__ __forceinline__ void swa_item(LAS unsigned char* lds, const GAS bf16_t* proj, GAS bf16_t* mix, const GAS float* sinks, int nb, int hk, int tid, int w, int lane) {
;     ...
;         if (nb == 0) {
; #pragma unroll
;             for (int j = 0; j < 9; ++j)
; #pragma unroll
;                 for (int i = 0; i < 4; ++i) s[j][i] = (16 * (w + j) + 4 * fq + i) >= 128 ? s[j][i] : -1e30f;
;         }
	v_readlane_b32 s0, v254, 48
	v_readlane_b32 s1, v254, 49
	v_cndmask_b32_e64 v22, v238, v22, s[66:67]
	v_cndmask_b32_e64 v23, v238, v23, s[68:69]
	v_cndmask_b32_e64 v41, v238, v41, s[0:1]
	v_readlane_b32 s0, v254, 53
	v_readlane_b32 s1, v254, 54
	v_cndmask_b32_e64 v12, v238, v12, s[70:71]
	v_cndmask_b32_e64 v13, v238, v13, s[72:73]
	v_cndmask_b32_e64 v40, v238, v40, s[0:1]
	v_readlane_b32 s0, v255, 4
	v_readlane_b32 s1, v255, 5
	v_cndmask_b32_e64 v14, v238, v14, s[74:75]
	v_cndmask_b32_e64 v15, v238, v15, s[76:77]
	v_cndmask_b32_e64 v11, v238, v11, s[0:1]
	v_readlane_b32 s0, v255, 6
	v_readlane_b32 s1, v255, 7
	v_cndmask_b32_e64 v16, v238, v16, s[78:79]
	v_cndmask_b32_e64 v17, v238, v17, s[80:81]
	v_cndmask_b32_e64 v10, v238, v10, s[0:1]
	v_readlane_b32 s0, v255, 8
	v_readlane_b32 s1, v255, 9
	v_cndmask_b32_e64 v18, v238, v18, s[82:83]
	v_cndmask_b32_e64 v19, v238, v19, s[26:27]
	v_cndmask_b32_e64 v36, v238, v36, s[0:1]
	v_readlane_b32 s0, v255, 10
	v_readlane_b32 s1, v255, 11
	v_cndmask_b32_e64 v9, v238, v9, s[28:29]
	v_cndmask_b32_e64 v8, v238, v8, s[52:53]
	v_cndmask_b32_e64 v37, v238, v37, s[0:1]
	v_readlane_b32 s0, v255, 12
	v_readlane_b32 s1, v255, 13
	v_cndmask_b32_e64 v7, v238, v7, s[54:55]
	v_cndmask_b32_e64 v6, v238, v6, s[56:57]
	v_cndmask_b32_e64 v38, v238, v38, s[0:1]
	v_readlane_b32 s0, v255, 14
	v_readlane_b32 s1, v255, 15
	s_nop 1
	v_cndmask_b32_e64 v39, v238, v39, s[0:1]
	v_readlane_b32 s0, v255, 16
	v_readlane_b32 s1, v255, 17
	s_nop 1
	v_cndmask_b32_e64 v32, v238, v32, s[0:1]
	v_readlane_b32 s0, v255, 18
	v_readlane_b32 s1, v255, 19
	s_nop 1
	v_cndmask_b32_e64 v33, v238, v33, s[0:1]
	v_readlane_b32 s0, v255, 20
	v_readlane_b32 s1, v255, 21
	s_nop 1
	v_cndmask_b32_e64 v34, v238, v34, s[0:1]
	v_readlane_b32 s0, v255, 22
	v_readlane_b32 s1, v255, 23
	s_nop 1
	v_cndmask_b32_e64 v35, v238, v35, s[0:1]
	v_readlane_b32 s0, v255, 24
	v_readlane_b32 s1, v255, 25
	s_nop 1
	v_cndmask_b32_e64 v28, v238, v28, s[0:1]
	v_readlane_b32 s0, v255, 26
	v_readlane_b32 s1, v255, 27
	s_nop 1
	v_cndmask_b32_e64 v29, v238, v29, s[0:1]
	v_readlane_b32 s0, v255, 28
	v_readlane_b32 s1, v255, 29
	s_nop 1
	v_cndmask_b32_e64 v30, v238, v30, s[0:1]
	v_readlane_b32 s0, v255, 30
	v_readlane_b32 s1, v255, 31
	s_nop 1
	v_cndmask_b32_e64 v31, v238, v31, s[0:1]
	v_readlane_b32 s0, v255, 32
	v_readlane_b32 s1, v255, 33
	s_nop 1
	v_cndmask_b32_e64 v24, v238, v24, s[0:1]
	v_readlane_b32 s0, v255, 34
	v_readlane_b32 s1, v255, 35
	s_nop 1
	v_cndmask_b32_e64 v25, v238, v25, s[0:1]
	v_readlane_b32 s0, v255, 36
	v_readlane_b32 s1, v255, 37
	s_nop 1
	v_cndmask_b32_e64 v26, v238, v26, s[0:1]
	v_readlane_b32 s0, v255, 38
	v_readlane_b32 s1, v255, 39
	s_nop 1
	v_cndmask_b32_e64 v27, v238, v27, s[0:1]
	v_readlane_b32 s0, v255, 40
	v_readlane_b32 s1, v255, 41
	s_nop 1
	v_cndmask_b32_e64 v20, v238, v20, s[0:1]
	v_readlane_b32 s0, v255, 42
	v_readlane_b32 s1, v255, 43
	s_nop 1
	v_cndmask_b32_e64 v21, v238, v21, s[0:1]
	s_branch .LBB0_411

; #define GAS __attribute__((address_space(1)))
; __device__ __forceinline__ size_t PJ(int row, int col) { return ((size_t)(col >> 6) * SEQ + row) * 64 + (col & 63); }
; __device__ __forceinline__ void conv_phase(const GAS bf16_t* proj, const GAS float* cw, const GAS float* cb_, GAS bf16_t* mix, int tid, int G, int bid) {
;     ...
;         const int it = (G == 256) ? (((512 * (bid & 7) + 16 * (bid >> 3)) << 5) + tid) : it0;
;         const int t0 = (it >> 5) * 4, c8 = (it & 31) * 8;
;         u32x4 ccr[6], cur[6], cbr[4];
; #pragma unroll
;         for (int r = 0; r < 6; ++r) { const int tt = t0 - 2 + r;
;             ccr[r] = (u32x4){0u, 0u, 0u, 0u}; cur[r] = (u32x4){0u, 0u, 0u, 0u};
;             if (tt >= 0) { ccr[r] = *(const GAS u32x4*)(proj + PJ(tt, C_CC + c8)); cur[r] = *(const GAS u32x4*)(proj + PJ(tt, C_CU + c8)); } }
.LBB0_437:
	s_waitcnt vmcnt(12)
	v_cndmask_b32_e64 v100, v1, v98, s[62:63]
	s_waitcnt lgkmcnt(0)
	v_lshlrev_b32_e32 v3, 3, v100
	v_and_b32_e32 v14, 0xf8, v3
	v_lshlrev_b32_e32 v15, 14, v14
	v_add_u32_e32 v4, 0x2600000, v15
	v_and_b32_e32 v4, 0x2f00000, v4
	v_and_b32_e32 v3, 56, v3
	v_lshlrev_b32_e32 v178, 1, v4
	v_lshl_add_u64 v[4:5], s[94:95], 0, v[178:179]
	v_lshlrev_b32_e32 v178, 1, v3
	v_add_u32_e32 v3, 0x2a00000, v15
	v_and_b32_e32 v3, 0x2f00000, v3
	v_lshlrev_b32_e32 v6, 1, v3
	v_mov_b32_e32 v7, v179
	v_ashrrev_i32_e32 v99, 3, v100
	v_lshl_add_u64 v[6:7], s[94:95], 0, v[6:7]
	v_and_b32_e32 v2, -4, v99
	v_lshl_add_u64 v[4:5], v[4:5], 0, v[178:179]
	v_lshl_add_u64 v[6:7], v[6:7], 0, v[178:179]
	v_cmp_lt_i32_e32 vcc, 3, v99
	v_mov_b32_e32 v38, 0
	v_mov_b32_e32 v50, 0
	v_mov_b32_e32 v51, 0
	v_mov_b32_e32 v52, 0
	v_mov_b32_e32 v53, 0
	v_mov_b32_e32 v54, 0
	v_mov_b32_e32 v55, 0
	v_mov_b32_e32 v56, 0
	v_mov_b32_e32 v57, 0
	s_and_saveexec_b64 s[8:9], vcc
	s_cbranch_execz .LBB0_439
	v_add_u32_e32 v8, -2, v2
	v_mov_b32_e32 v9, v179
	v_lshlrev_b64 v[8:9], 7, v[8:9]
	v_lshl_add_u64 v[10:11], v[6:7], 0, v[8:9]
	v_lshl_add_u64 v[8:9], v[4:5], 0, v[8:9]
	v_mov_b32_e32 v54, v154
	v_mov_b32_e32 v55, v155
	v_mov_b32_e32 v56, v156
	v_mov_b32_e32 v57, v157
	v_mov_b32_e32 v50, v180
	v_mov_b32_e32 v51, v181
	v_mov_b32_e32 v52, v182
	v_mov_b32_e32 v53, v183
